# instruction selection in the attention softmax: packed f32 (v_pk_add_f32 / v_pk_mul_f32) for the bias add, max subtraction, row sum and O rescale (same f32 arithmetic, half the VALU instructions)
# speedup vs baseline: 1.0024x; 1.0024x over previous
; #define NEGINF (-__builtin_inff())
; DI float shx32(float v) { const auto r = __builtin_amdgcn_permlane32_swap(__float_as_uint(v), __float_as_uint(v), false, false); return __uint_as_float((threadIdx.x & 32) ? r[0] : r[1]); }
; DI float ex2(float x) { return __builtin_amdgcn_exp2f(x); }
; DI int crow(int i, int h) { return (i & 3) + 8 * (i >> 2) + 4 * h; }
; DI void softmax_step_r(AttnSt& st, const float (&lg)[16], const KVT& t) {
;   float mx = NEGINF;
; #pragma unroll
;   for (int i = 0; i < 16; ++i) mx = fmaxf(mx, lg[i]);
;   mx = fmaxf(mx, shx32(mx));
;   if (__ballot(mx > NEGINF) == 0ull) return;
;   const float mnew = fmaxf(st.m, mx);
;   const float muse = (mnew == NEGINF) ? 0.f : mnew;
;   const float alpha = ex2(st.m - muse);
;   float pr[16]; float rs = 0.f;
; #pragma unroll
;   for (int i = 0; i < 16; ++i) { pr[i] = ex2(lg[i] - muse); rs += pr[i]; }
;   st.l = st.l * alpha + rs;
;   if (__ballot(mnew != st.m) != 0ull) {
; #pragma unroll
;     for (int i = 0; i < 16; ++i) { st.o0[i] *= alpha; st.o1[i] *= alpha; }
;   }
;   st.m = mnew;
; DI void nsa_win_item(const Params& p, int b, int head, int qb, const unsigned char* blut, const float* tbl) {
;     ...
;       [&](int kt, const f32x16& s, float (&lg)[16]) {
;         int dist[16]; float bv[16];
; #pragma unroll
;         for (int i = 0; i < 16; ++i) dist[i] = t - (kt * 32 + crow(i, h));
;         bias16(blut, tblh, dist, bv);
; #pragma unroll
;         for (int i = 0; i < 16; ++i) lg[i] = (dist[i] >= 0 && dist[i] < 512) ? s[i] + bv[i] : NEGINF;
;       });
.Lawin6_loop:
	s_waitcnt vmcnt(2)
	s_barrier
	s_lshr_b32 s23, s56, 1
	s_add_u32 s23, s23, 2
	s_sub_u32 s61, s64, 0x4000
	s_cmp_lt_u32 s61, 0x10000
	s_cselect_b32 s61, 0x18000, s61
	s_lshr_b32 s24, s59, 1
	s_min_u32 s24, s23, s24
	s_lshl_b32 s26, s24, 13
	s_lshl_b32 s24, s58, 10
	s_add_u32 s26, s26, s24
	s_mov_b32 s27, 0
	v_lshl_add_u64 v[248:249], v[116:117], 0, s[26:27]
	v_lshl_add_u64 v[250:251], v[114:115], 0, s[26:27]
	v_add_co_u32_e32 v250, vcc, v250, v247
	v_addc_co_u32_e32 v251, vcc, 0, v251, vcc
	s_add_u32 s24, s24, s61
	s_mov_b32 m0, s24
	s_nop 0
	global_load_lds_dwordx4 v[248:249], off
	s_add_u32 s24, s24, 0x2000
	s_mov_b32 m0, s24
	s_nop 0
	global_load_lds_dwordx4 v[250:251], off
	s_cmp_le_u32 s56, s60
	s_cbranch_scc0 .Lawin6_skip
	s_add_u32 s24, s56, 1
	s_cmp_ge_u32 s24, s65
	s_cbranch_scc0 .Lawin6_skip
	v_lshl_add_u32 v248, v247, 1, s64
	ds_read_b128 v[80:83], v248 offset:0
	ds_read_b128 v[84:87], v248 offset:1024
	ds_read_b128 v[88:91], v248 offset:2048
	ds_read_b128 v[92:95], v248 offset:3072
	ds_read_b128 v[96:99], v248 offset:4096
	ds_read_b128 v[100:103], v248 offset:5120
	ds_read_b128 v[104:107], v248 offset:6144
	ds_read_b128 v[108:111], v248 offset:7168
	s_sub_i32 s61, s60, s56
	s_waitcnt lgkmcnt(0)
	v_mfma_f32_32x32x16_bf16 v[32:47], v[80:83], v[64:67], 0
	v_mfma_f32_32x32x16_bf16 v[48:63], v[96:99], v[64:67], 0
	v_mfma_f32_32x32x16_bf16 v[32:47], v[84:87], v[68:71], v[32:47]
	v_mfma_f32_32x32x16_bf16 v[48:63], v[100:103], v[68:71], v[48:63]
	v_mfma_f32_32x32x16_bf16 v[32:47], v[88:91], v[72:75], v[32:47]
	v_mfma_f32_32x32x16_bf16 v[48:63], v[104:107], v[72:75], v[48:63]
	v_mfma_f32_32x32x16_bf16 v[32:47], v[92:95], v[76:79], v[32:47]
	v_mfma_f32_32x32x16_bf16 v[48:63], v[108:111], v[76:79], v[48:63]
	v_add_u32_e32 v250, s64, v247
	ds_read_b64 v[146:147], v250 offset:8192
	ds_read_b64 v[148:149], v250 offset:8704
	ds_read_b64 v[150:151], v250 offset:9216
	ds_read_b64 v[152:153], v250 offset:9728
	ds_read_b64 v[154:155], v250 offset:10240
	ds_read_b64 v[156:157], v250 offset:10752
	ds_read_b64 v[158:159], v250 offset:11264
	ds_read_b64 v[160:161], v250 offset:11776
	ds_read_b64 v[162:163], v250 offset:12288
	ds_read_b64 v[164:165], v250 offset:12800
	ds_read_b64 v[166:167], v250 offset:13312
	ds_read_b64 v[168:169], v250 offset:13824
	ds_read_b64 v[170:171], v250 offset:14336
	ds_read_b64 v[172:173], v250 offset:14848
	ds_read_b64 v[174:175], v250 offset:15360
	ds_read_b64 v[176:177], v250 offset:15872
	s_cmp_ge_i32 s61, 50
	s_cbranch_scc1 .Lawin6_far
	s_lshl_b32 s23, s61, 5
	v_add_u32_e32 v241, s23, v222
	v_lshl_add_u32 v244, v241, 2, v242
	v_subrev_u32_e32 v245, 128, v244
	ds_read_b32 v224, v244 offset:108
	ds_read_b32 v225, v244 offset:104
	ds_read_b32 v226, v244 offset:100
	ds_read_b32 v227, v244 offset:96
	ds_read_b32 v228, v244 offset:76
	ds_read_b32 v229, v244 offset:72
	ds_read_b32 v230, v244 offset:68
	ds_read_b32 v231, v244 offset:64
	ds_read_b32 v232, v244 offset:44
	ds_read_b32 v233, v244 offset:40
	ds_read_b32 v234, v244 offset:36
	ds_read_b32 v235, v244 offset:32
	ds_read_b32 v236, v244 offset:12
	ds_read_b32 v237, v244 offset:8
	ds_read_b32 v238, v244 offset:4
	ds_read_b32 v239, v244 offset:0
	s_waitcnt lgkmcnt(8)
	v_pk_add_f32 v[32:33], v[32:33], v[224:225]
	v_pk_add_f32 v[34:35], v[34:35], v[226:227]
	v_pk_add_f32 v[36:37], v[36:37], v[228:229]
	v_pk_add_f32 v[38:39], v[38:39], v[230:231]
	s_waitcnt lgkmcnt(0)
	v_pk_add_f32 v[40:41], v[40:41], v[232:233]
	v_pk_add_f32 v[42:43], v[42:43], v[234:235]
	v_pk_add_f32 v[44:45], v[44:45], v[236:237]
	v_pk_add_f32 v[46:47], v[46:47], v[238:239]
	ds_read_b32 v224, v245 offset:108
	ds_read_b32 v225, v245 offset:104
	ds_read_b32 v226, v245 offset:100
	ds_read_b32 v227, v245 offset:96
	ds_read_b32 v228, v245 offset:76
	ds_read_b32 v229, v245 offset:72
	ds_read_b32 v230, v245 offset:68
	ds_read_b32 v231, v245 offset:64
	ds_read_b32 v232, v245 offset:44
	ds_read_b32 v233, v245 offset:40
	ds_read_b32 v234, v245 offset:36
	ds_read_b32 v235, v245 offset:32
	ds_read_b32 v236, v245 offset:12
	ds_read_b32 v237, v245 offset:8
	ds_read_b32 v238, v245 offset:4
	ds_read_b32 v239, v245 offset:0
	s_waitcnt lgkmcnt(8)
	v_pk_add_f32 v[48:49], v[48:49], v[224:225]
	v_pk_add_f32 v[50:51], v[50:51], v[226:227]
	v_pk_add_f32 v[52:53], v[52:53], v[228:229]
	v_pk_add_f32 v[54:55], v[54:55], v[230:231]
	s_waitcnt lgkmcnt(0)
	v_pk_add_f32 v[56:57], v[56:57], v[232:233]
	v_pk_add_f32 v[58:59], v[58:59], v[234:235]
	v_pk_add_f32 v[60:61], v[60:61], v[236:237]
	v_pk_add_f32 v[62:63], v[62:63], v[238:239]
	s_cmp_ge_i32 s61, 15
	s_cbranch_scc0 .Lawin6_nowin
; #define NEGINF (-__builtin_inff())
; DI int crow(int i, int h) { return (i & 3) + 8 * (i >> 2) + 4 * h; }
; DI void nsa_win_item(const Params& p, int b, int head, int qb, const unsigned char* blut, const float* tbl) {
;     ...
;       [&](int kt, const f32x16& s, float (&lg)[16]) {
;         int dist[16]; float bv[16];
; #pragma unroll
;         for (int i = 0; i < 16; ++i) dist[i] = t - (kt * 32 + crow(i, h));
;         bias16(blut, tblh, dist, bv);
; #pragma unroll
;         for (int i = 0; i < 16; ++i) lg[i] = (dist[i] >= 0 && dist[i] < 512) ? s[i] + bv[i] : NEGINF;
;       });
	v_subrev_u32_e32 v246, 32, v241
	v_cmp_gt_i32_e32 vcc, 0x200, v241
	s_nop 1
	v_cndmask_b32_e32 v32, v199, v32, vcc
	v_cmp_gt_i32_e32 vcc, 0x201, v241
	s_nop 1
	v_cndmask_b32_e32 v33, v199, v33, vcc
	v_cmp_gt_i32_e32 vcc, 0x202, v241
	s_nop 1
	v_cndmask_b32_e32 v34, v199, v34, vcc
	v_cmp_gt_i32_e32 vcc, 0x203, v241
	s_nop 1
	v_cndmask_b32_e32 v35, v199, v35, vcc
	v_cmp_gt_i32_e32 vcc, 0x208, v241
	s_nop 1
	v_cndmask_b32_e32 v36, v199, v36, vcc
	v_cmp_gt_i32_e32 vcc, 0x209, v241
	s_nop 1
	v_cndmask_b32_e32 v37, v199, v37, vcc
	v_cmp_gt_i32_e32 vcc, 0x20a, v241
	s_nop 1
	v_cndmask_b32_e32 v38, v199, v38, vcc
	v_cmp_gt_i32_e32 vcc, 0x20b, v241
	s_nop 1
	v_cndmask_b32_e32 v39, v199, v39, vcc
	v_cmp_gt_i32_e32 vcc, 0x210, v241
	s_nop 1
	v_cndmask_b32_e32 v40, v199, v40, vcc
	v_cmp_gt_i32_e32 vcc, 0x211, v241
	s_nop 1
	v_cndmask_b32_e32 v41, v199, v41, vcc
	v_cmp_gt_i32_e32 vcc, 0x212, v241
	s_nop 1
	v_cndmask_b32_e32 v42, v199, v42, vcc
	v_cmp_gt_i32_e32 vcc, 0x213, v241
	s_nop 1
	v_cndmask_b32_e32 v43, v199, v43, vcc
	v_cmp_gt_i32_e32 vcc, 0x218, v241
	s_nop 1
	v_cndmask_b32_e32 v44, v199, v44, vcc
	v_cmp_gt_i32_e32 vcc, 0x219, v241
	s_nop 1
	v_cndmask_b32_e32 v45, v199, v45, vcc
	v_cmp_gt_i32_e32 vcc, 0x21a, v241
	s_nop 1
	v_cndmask_b32_e32 v46, v199, v46, vcc
	v_cmp_gt_i32_e32 vcc, 0x21b, v241
	s_nop 1
	v_cndmask_b32_e32 v47, v199, v47, vcc
	v_cmp_gt_i32_e32 vcc, 0x200, v246
	s_nop 1
	v_cndmask_b32_e32 v48, v199, v48, vcc
	v_cmp_gt_i32_e32 vcc, 0x201, v246
	s_nop 1
	v_cndmask_b32_e32 v49, v199, v49, vcc
	v_cmp_gt_i32_e32 vcc, 0x202, v246
	s_nop 1
	v_cndmask_b32_e32 v50, v199, v50, vcc
	v_cmp_gt_i32_e32 vcc, 0x203, v246
	s_nop 1
	v_cndmask_b32_e32 v51, v199, v51, vcc
	v_cmp_gt_i32_e32 vcc, 0x208, v246
	s_nop 1
	v_cndmask_b32_e32 v52, v199, v52, vcc
	v_cmp_gt_i32_e32 vcc, 0x209, v246
	s_nop 1
	v_cndmask_b32_e32 v53, v199, v53, vcc
	v_cmp_gt_i32_e32 vcc, 0x20a, v246
	s_nop 1
	v_cndmask_b32_e32 v54, v199, v54, vcc
	v_cmp_gt_i32_e32 vcc, 0x20b, v246
	s_nop 1
	v_cndmask_b32_e32 v55, v199, v55, vcc
	v_cmp_gt_i32_e32 vcc, 0x210, v246
	s_nop 1
	v_cndmask_b32_e32 v56, v199, v56, vcc
	v_cmp_gt_i32_e32 vcc, 0x211, v246
	s_nop 1
	v_cndmask_b32_e32 v57, v199, v57, vcc
	v_cmp_gt_i32_e32 vcc, 0x212, v246
	s_nop 1
	v_cndmask_b32_e32 v58, v199, v58, vcc
	v_cmp_gt_i32_e32 vcc, 0x213, v246
	s_nop 1
	v_cndmask_b32_e32 v59, v199, v59, vcc
	v_cmp_gt_i32_e32 vcc, 0x218, v246
	s_nop 1
	v_cndmask_b32_e32 v60, v199, v60, vcc
	v_cmp_gt_i32_e32 vcc, 0x219, v246
	s_nop 1
	v_cndmask_b32_e32 v61, v199, v61, vcc
	v_cmp_gt_i32_e32 vcc, 0x21a, v246
	s_nop 1
	v_cndmask_b32_e32 v62, v199, v62, vcc
	v_cmp_gt_i32_e32 vcc, 0x21b, v246
	s_nop 1
	v_cndmask_b32_e32 v63, v199, v63, vcc

; #define MFMA32(a, b, c) __builtin_amdgcn_mfma_f32_32x32x16_bf16((a), (b), (c), 0, 0, 0)
; #define NEGINF (-__builtin_inff())
; DI float shx32(float v) { const auto r = __builtin_amdgcn_permlane32_swap(__float_as_uint(v), __float_as_uint(v), false, false); return __uint_as_float((threadIdx.x & 32) ? r[0] : r[1]); }
; DI float ex2(float x) { return __builtin_amdgcn_exp2f(x); }
; DI unsigned pack2(float a, float b) { unsigned r; asm("v_cvt_pk_bf16_f32 %0, %1, %2" : "=v"(r) : "v"(a), "v"(b)); return r; }
; DI void softmax_step_r(AttnSt& st, const float (&lg)[16], const KVT& t) {
;   float mx = NEGINF;
; #pragma unroll
;   for (int i = 0; i < 16; ++i) mx = fmaxf(mx, lg[i]);
;   mx = fmaxf(mx, shx32(mx));
;   if (__ballot(mx > NEGINF) == 0ull) return;
;   const float mnew = fmaxf(st.m, mx);
;   const float muse = (mnew == NEGINF) ? 0.f : mnew;
;   const float alpha = ex2(st.m - muse);
;   float pr[16]; float rs = 0.f;
; #pragma unroll
;   for (int i = 0; i < 16; ++i) { pr[i] = ex2(lg[i] - muse); rs += pr[i]; }
;   st.l = st.l * alpha + rs;
;   if (__ballot(mnew != st.m) != 0ull) {
; #pragma unroll
;     for (int i = 0; i < 16; ++i) { st.o0[i] *= alpha; st.o1[i] *= alpha; }
;   }
;   st.m = mnew;
; #pragma unroll
;   for (int s2 = 0; s2 < 2; ++s2) {
;     u32x4 pk; pk.x = pack2(pr[8 * s2], pr[8 * s2 + 1]); pk.y = pack2(pr[8 * s2 + 2], pr[8 * s2 + 3]); pk.z = pack2(pr[8 * s2 + 4], pr[8 * s2 + 5]); pk.w = pack2(pr[8 * s2 + 6], pr[8 * s2 + 7]);
;     const bf16x8 pb = __builtin_bit_cast(bf16x8, pk);
;     const bf16x8 va0 = __builtin_shufflevector(t.v[s2 * 4 + 0], t.v[s2 * 4 + 1], 0, 1, 2, 3, 4, 5, 6, 7);
;     st.o0 = MFMA32(va0, pb, st.o0);
;     const bf16x8 va1 = __builtin_shufflevector(t.v[s2 * 4 + 2], t.v[s2 * 4 + 3], 0, 1, 2, 3, 4, 5, 6, 7);
;     st.o1 = MFMA32(va1, pb, st.o1);
.Lawin6_far:
	s_nop 7
	v_pk_add_f32 v[32:33], v[32:33], v[240:241] op_sel_hi:[1,0]
	v_pk_add_f32 v[34:35], v[34:35], v[240:241] op_sel_hi:[1,0]
	v_pk_add_f32 v[36:37], v[36:37], v[240:241] op_sel_hi:[1,0]
	v_pk_add_f32 v[38:39], v[38:39], v[240:241] op_sel_hi:[1,0]
	v_pk_add_f32 v[40:41], v[40:41], v[240:241] op_sel_hi:[1,0]
	v_pk_add_f32 v[42:43], v[42:43], v[240:241] op_sel_hi:[1,0]
	v_pk_add_f32 v[44:45], v[44:45], v[240:241] op_sel_hi:[1,0]
	v_pk_add_f32 v[46:47], v[46:47], v[240:241] op_sel_hi:[1,0]
	v_pk_add_f32 v[48:49], v[48:49], v[240:241] op_sel_hi:[1,0]
	v_pk_add_f32 v[50:51], v[50:51], v[240:241] op_sel_hi:[1,0]
	v_pk_add_f32 v[52:53], v[52:53], v[240:241] op_sel_hi:[1,0]
	v_pk_add_f32 v[54:55], v[54:55], v[240:241] op_sel_hi:[1,0]
	v_pk_add_f32 v[56:57], v[56:57], v[240:241] op_sel_hi:[1,0]
	v_pk_add_f32 v[58:59], v[58:59], v[240:241] op_sel_hi:[1,0]
	v_pk_add_f32 v[60:61], v[60:61], v[240:241] op_sel_hi:[1,0]
	v_pk_add_f32 v[62:63], v[62:63], v[240:241] op_sel_hi:[1,0]
.Lawin6_softmax:
	v_max3_f32 v224, v32, v33, v34
	v_max3_f32 v225, v40, v41, v42
	v_max3_f32 v226, v48, v49, v50
	v_max3_f32 v227, v56, v57, v58
	v_max3_f32 v224, v224, v35, v36
	v_max3_f32 v225, v225, v43, v44
	v_max3_f32 v226, v226, v51, v52
	v_max3_f32 v227, v227, v59, v60
	v_max3_f32 v224, v224, v37, v38
	v_max3_f32 v225, v225, v45, v46
	v_max3_f32 v226, v226, v53, v54
	v_max3_f32 v227, v227, v61, v62
	v_max_f32_e32 v224, v224, v39
	v_max_f32_e32 v225, v225, v47
	v_max_f32_e32 v226, v226, v55
	v_max_f32_e32 v227, v227, v63
	v_max3_f32 v224, v224, v225, v226
	v_max_f32_e32 v224, v224, v227
	v_mov_b32_e32 v225, v224
	v_mov_b32_e32 v226, v224
	s_nop 1
	v_permlane32_swap_b32_e32 v225, v226
	v_cndmask_b32_e64 v225, v225, v226, s[12:13]
	v_max_f32_e32 v224, v224, v225
	v_cndmask_b32_e64 v224, v199, v224, s[62:63]
	v_max_f32_e32 v225, v223, v224
	v_cmp_neq_f32_e32 vcc, v199, v225
	s_nop 1
	v_cndmask_b32_e32 v226, 0, v225, vcc
	v_sub_f32_e32 v227, v223, v226
	v_exp_f32_e32 v227, v227
	v_cndmask_b32_e64 v226, v243, v226, s[62:63]
	v_cmp_neq_f32_e32 vcc, v223, v225
	v_mov_b32_e32 v223, v225
	v_pk_add_f32 v[32:33], v[32:33], v[226:227] op_sel_hi:[1,0] neg_lo:[0,1] neg_hi:[0,1]
	v_pk_add_f32 v[34:35], v[34:35], v[226:227] op_sel_hi:[1,0] neg_lo:[0,1] neg_hi:[0,1]
	v_pk_add_f32 v[36:37], v[36:37], v[226:227] op_sel_hi:[1,0] neg_lo:[0,1] neg_hi:[0,1]
	v_pk_add_f32 v[38:39], v[38:39], v[226:227] op_sel_hi:[1,0] neg_lo:[0,1] neg_hi:[0,1]
	v_pk_add_f32 v[40:41], v[40:41], v[226:227] op_sel_hi:[1,0] neg_lo:[0,1] neg_hi:[0,1]
	v_pk_add_f32 v[42:43], v[42:43], v[226:227] op_sel_hi:[1,0] neg_lo:[0,1] neg_hi:[0,1]
	v_pk_add_f32 v[44:45], v[44:45], v[226:227] op_sel_hi:[1,0] neg_lo:[0,1] neg_hi:[0,1]
	v_pk_add_f32 v[46:47], v[46:47], v[226:227] op_sel_hi:[1,0] neg_lo:[0,1] neg_hi:[0,1]
	v_pk_add_f32 v[48:49], v[48:49], v[226:227] op_sel_hi:[1,0] neg_lo:[0,1] neg_hi:[0,1]
	v_pk_add_f32 v[50:51], v[50:51], v[226:227] op_sel_hi:[1,0] neg_lo:[0,1] neg_hi:[0,1]
	v_pk_add_f32 v[52:53], v[52:53], v[226:227] op_sel_hi:[1,0] neg_lo:[0,1] neg_hi:[0,1]
	v_pk_add_f32 v[54:55], v[54:55], v[226:227] op_sel_hi:[1,0] neg_lo:[0,1] neg_hi:[0,1]
	v_pk_add_f32 v[56:57], v[56:57], v[226:227] op_sel_hi:[1,0] neg_lo:[0,1] neg_hi:[0,1]
	v_pk_add_f32 v[58:59], v[58:59], v[226:227] op_sel_hi:[1,0] neg_lo:[0,1] neg_hi:[0,1]
	v_pk_add_f32 v[60:61], v[60:61], v[226:227] op_sel_hi:[1,0] neg_lo:[0,1] neg_hi:[0,1]
	v_pk_add_f32 v[62:63], v[62:63], v[226:227] op_sel_hi:[1,0] neg_lo:[0,1] neg_hi:[0,1]
	v_exp_f32_e32 v32, v32
	v_exp_f32_e32 v33, v33
	v_exp_f32_e32 v34, v34
	v_exp_f32_e32 v35, v35
	v_exp_f32_e32 v36, v36
	v_exp_f32_e32 v37, v37
	v_exp_f32_e32 v38, v38
	v_exp_f32_e32 v39, v39
	v_exp_f32_e32 v40, v40
	v_exp_f32_e32 v41, v41
	v_exp_f32_e32 v42, v42
	v_exp_f32_e32 v43, v43
	v_exp_f32_e32 v44, v44
	v_exp_f32_e32 v45, v45
	v_exp_f32_e32 v46, v46
	v_exp_f32_e32 v47, v47
	v_exp_f32_e32 v48, v48
	v_exp_f32_e32 v49, v49
	v_exp_f32_e32 v50, v50
	v_exp_f32_e32 v51, v51
	v_exp_f32_e32 v52, v52
	v_exp_f32_e32 v53, v53
	v_exp_f32_e32 v54, v54
	v_exp_f32_e32 v55, v55
	v_exp_f32_e32 v56, v56
	v_exp_f32_e32 v57, v57
	v_exp_f32_e32 v58, v58
	v_exp_f32_e32 v59, v59
	v_exp_f32_e32 v60, v60
	v_exp_f32_e32 v61, v61
	v_exp_f32_e32 v62, v62
	v_exp_f32_e32 v63, v63
	v_pk_add_f32 v[228:229], v[32:33], v[34:35]
	v_pk_add_f32 v[230:231], v[36:37], v[38:39]
	v_pk_add_f32 v[228:229], v[228:229], v[40:41]
	v_pk_add_f32 v[230:231], v[230:231], v[42:43]
	v_pk_add_f32 v[228:229], v[228:229], v[44:45]
	v_pk_add_f32 v[230:231], v[230:231], v[46:47]
	v_pk_add_f32 v[228:229], v[228:229], v[48:49]
	v_pk_add_f32 v[230:231], v[230:231], v[50:51]
	v_pk_add_f32 v[228:229], v[228:229], v[52:53]
	v_pk_add_f32 v[230:231], v[230:231], v[54:55]
	v_pk_add_f32 v[228:229], v[228:229], v[56:57]
	v_pk_add_f32 v[230:231], v[230:231], v[58:59]
	v_pk_add_f32 v[228:229], v[228:229], v[60:61]
	v_pk_add_f32 v[230:231], v[230:231], v[62:63]
	v_pk_add_f32 v[228:229], v[228:229], v[230:231]
	v_add_f32_e32 v228, v228, v229
	v_fma_f32 v145, v145, v227, v228
	s_cbranch_vccz .Lawin6_noscale
	v_pk_mul_f32 v[0:1], v[0:1], v[226:227] op_sel:[0,1] op_sel_hi:[1,1]
	v_pk_mul_f32 v[2:3], v[2:3], v[226:227] op_sel:[0,1] op_sel_hi:[1,1]
	v_pk_mul_f32 v[4:5], v[4:5], v[226:227] op_sel:[0,1] op_sel_hi:[1,1]
	v_pk_mul_f32 v[6:7], v[6:7], v[226:227] op_sel:[0,1] op_sel_hi:[1,1]
	v_pk_mul_f32 v[8:9], v[8:9], v[226:227] op_sel:[0,1] op_sel_hi:[1,1]
	v_pk_mul_f32 v[10:11], v[10:11], v[226:227] op_sel:[0,1] op_sel_hi:[1,1]
	v_pk_mul_f32 v[12:13], v[12:13], v[226:227] op_sel:[0,1] op_sel_hi:[1,1]
	v_pk_mul_f32 v[14:15], v[14:15], v[226:227] op_sel:[0,1] op_sel_hi:[1,1]
	v_pk_mul_f32 v[16:17], v[16:17], v[226:227] op_sel:[0,1] op_sel_hi:[1,1]
	v_pk_mul_f32 v[18:19], v[18:19], v[226:227] op_sel:[0,1] op_sel_hi:[1,1]
	v_pk_mul_f32 v[20:21], v[20:21], v[226:227] op_sel:[0,1] op_sel_hi:[1,1]
	v_pk_mul_f32 v[22:23], v[22:23], v[226:227] op_sel:[0,1] op_sel_hi:[1,1]
	v_pk_mul_f32 v[24:25], v[24:25], v[226:227] op_sel:[0,1] op_sel_hi:[1,1]
	v_pk_mul_f32 v[26:27], v[26:27], v[226:227] op_sel:[0,1] op_sel_hi:[1,1]
	v_pk_mul_f32 v[28:29], v[28:29], v[226:227] op_sel:[0,1] op_sel_hi:[1,1]
	v_pk_mul_f32 v[30:31], v[30:31], v[226:227] op_sel:[0,1] op_sel_hi:[1,1]

; #define MFMA32(a, b, c) __builtin_amdgcn_mfma_f32_32x32x16_bf16((a), (b), (c), 0, 0, 0)
; #define NEGINF (-__builtin_inff())
; DI int crow(int i, int h) { return (i & 3) + 8 * (i >> 2) + 4 * h; }
; template <class KP, class VP, class ACT, class FILL>
; DI void attn_loop(AttnSt& st, const bf16x8 (&qf)[4], int k0, int k1, size_t vstride, KP kp, VP vp, ACT act, FILL fill) {
;     ...
;   for (int kt = k0; kt <= k1; ++kt) {
;     const int kn = (kt < k1) ? kt + 1 : k1;
;     const int kn2 = (kt + 2 <= k1) ? kt + 2 : k1;
;     {
;       const bf16_t* v0 = vp(kn);
; #pragma unroll
;       for (int j = 0; j < 8; ++j) nxt.v[j] = *(const s16x4*)(v0 + 256 * j);
;     }
;     bf16x8 k2[4];
;     {
;       const bf16_t* krow = kp(kn2);
; #pragma unroll
;       for (int ss = 0; ss < 4; ++ss) k2[ss] = *(const bf16x8*)(krow + 512 * ss);
;     }
;     f32x16 s_next;
; #pragma unroll
;     for (int i = 0; i < 16; ++i) s_next[i] = 0.f;
; #pragma unroll
;     for (int ss = 0; ss < 4; ++ss) s_next = MFMA32(nxt.k[ss], qf[ss], s_next);
;     if (act(kt)) {
;       float lg[16];
;       fill(kt, s_cur, lg);
;       softmax_step_r(st, lg, cur);
;     }
; DI void nsa_main_item(const Params& p, int b, int head, int qb, const unsigned char* blut, const float* tbl) {
;     ...
;     attn_loop(st, qf, 0, qb, 32,
;       [&](int kt) { return K + (size_t)kt * 2048 + (h * 32 + r) * 8; },
;       [&](int kt) { return Vt + (size_t)kt * 2048 + (h * 32 + r) * 4; },
;       [&](int kt) { return __ballot((selm >> (kt >> 1)) & 1ull) != 0ull; },
;       [&](int kt, const f32x16& s, float (&lg)[16]) {
;         const bool bs = (selm >> (kt >> 1)) & 1ull;
;         if (qb * 32 - (kt * 32 + 31) >= 1513) {
;           const float b31 = tblh[31];
; #pragma unroll
;           for (int i = 0; i < 16; ++i) lg[i] = bs ? s[i] + b31 : NEGINF;
;         } else {
;           int dist[16]; float bv[16];
; #pragma unroll
;           for (int i = 0; i < 16; ++i) dist[i] = t - (kt * 32 + crow(i, h));
;           bias16(blut, tblh, dist, bv);
; #pragma unroll
;           for (int i = 0; i < 16; ++i) lg[i] = (bs && dist[i] >= 0) ? s[i] + bv[i] : NEGINF;
;         }
;       });
.Lasel_loop:
	s_waitcnt vmcnt(2)
	s_barrier
	s_lshr_b32 s23, s56, 1
	s_add_u32 s23, s23, 2
	s_sub_u32 s61, s100, 0x4000
	s_cmp_lt_u32 s61, 0x10000
	s_cselect_b32 s61, 0x18000, s61
	s_lshr_b32 s24, s59, 1
	s_min_u32 s24, s23, s24
	s_lshl_b32 s26, s24, 13
	s_lshl_b32 s24, s58, 10
	s_add_u32 s26, s26, s24
	s_mov_b32 s27, 0
	v_lshl_add_u64 v[248:249], v[148:149], 0, s[26:27]
	v_lshl_add_u64 v[250:251], v[170:171], 0, s[26:27]
	v_add_co_u32_e32 v250, vcc, v250, v247
	v_addc_co_u32_e32 v251, vcc, 0, v251, vcc
	s_add_u32 s24, s24, s61
	s_mov_b32 m0, s24
	s_nop 0
	global_load_lds_dwordx4 v[248:249], off
	s_add_u32 s24, s24, 0x2000
	s_mov_b32 m0, s24
	s_nop 0
	global_load_lds_dwordx4 v[250:251], off
	s_cmp_le_u32 s56, s60
	s_cbranch_scc0 .Lasel_skip
	v_lshl_add_u32 v248, v247, 1, s100
	ds_read_b128 v[96:99], v248 offset:0
	ds_read_b128 v[100:103], v248 offset:1024
	ds_read_b128 v[104:107], v248 offset:2048
	ds_read_b128 v[108:111], v248 offset:3072
	ds_read_b128 v[112:115], v248 offset:4096
	ds_read_b128 v[116:119], v248 offset:5120
	ds_read_b128 v[120:123], v248 offset:6144
	ds_read_b128 v[124:127], v248 offset:7168
	s_sub_i32 s61, s60, s56
	s_lshr_b32 s23, s56, 1
	v_lshrrev_b64 v[248:249], s23, v[168:169]
	v_and_b32_e32 v248, 1, v248
	v_cmp_eq_u32_e64 s[62:63], 1, v248
	s_waitcnt lgkmcnt(0)
	v_mfma_f32_32x32x16_bf16 v[32:47], v[96:99], v[80:83], 0
	v_mfma_f32_32x32x16_bf16 v[48:63], v[112:115], v[80:83], 0
	v_mfma_f32_32x32x16_bf16 v[32:47], v[100:103], v[84:87], v[32:47]
	v_mfma_f32_32x32x16_bf16 v[48:63], v[116:119], v[84:87], v[48:63]
	v_mfma_f32_32x32x16_bf16 v[32:47], v[104:107], v[88:91], v[32:47]
	v_mfma_f32_32x32x16_bf16 v[48:63], v[120:123], v[88:91], v[48:63]
	v_mfma_f32_32x32x16_bf16 v[32:47], v[108:111], v[92:95], v[32:47]
	v_mfma_f32_32x32x16_bf16 v[48:63], v[124:127], v[92:95], v[48:63]
	v_add_u32_e32 v250, s100, v247
	ds_read_b64 v[64:65], v250 offset:8192
	ds_read_b64 v[66:67], v250 offset:8704
	ds_read_b64 v[68:69], v250 offset:9216
	ds_read_b64 v[70:71], v250 offset:9728
	ds_read_b64 v[72:73], v250 offset:10240
	ds_read_b64 v[74:75], v250 offset:10752
	ds_read_b64 v[76:77], v250 offset:11264
	ds_read_b64 v[78:79], v250 offset:11776
	ds_read_b64 v[172:173], v250 offset:12288
	ds_read_b64 v[174:175], v250 offset:12800
	ds_read_b64 v[176:177], v250 offset:13312
	ds_read_b64 v[178:179], v250 offset:13824
	ds_read_b64 v[180:181], v250 offset:14336
	ds_read_b64 v[182:183], v250 offset:14848
	ds_read_b64 v[184:185], v250 offset:15360
	ds_read_b64 v[186:187], v250 offset:15872
	s_cmp_ge_i32 s61, 50
	s_cbranch_scc1 .Lasel_far
	s_lshl_b32 s23, s61, 5
	v_add_u32_e32 v241, s23, v221
	v_lshl_add_u32 v244, v241, 2, v242
	v_subrev_u32_e32 v245, 128, v244
	ds_read_b32 v224, v244 offset:108
	ds_read_b32 v225, v244 offset:104
	ds_read_b32 v226, v244 offset:100
	ds_read_b32 v227, v244 offset:96
	ds_read_b32 v228, v244 offset:76
	ds_read_b32 v229, v244 offset:72
	ds_read_b32 v230, v244 offset:68
	ds_read_b32 v231, v244 offset:64
	ds_read_b32 v232, v244 offset:44
	ds_read_b32 v233, v244 offset:40
	ds_read_b32 v234, v244 offset:36
	ds_read_b32 v235, v244 offset:32
	ds_read_b32 v236, v244 offset:12
	ds_read_b32 v237, v244 offset:8
	ds_read_b32 v238, v244 offset:4
	ds_read_b32 v239, v244 offset:0
	s_waitcnt lgkmcnt(8)
	v_pk_add_f32 v[32:33], v[32:33], v[224:225]
	v_pk_add_f32 v[34:35], v[34:35], v[226:227]
	v_pk_add_f32 v[36:37], v[36:37], v[228:229]
	v_pk_add_f32 v[38:39], v[38:39], v[230:231]
	s_waitcnt lgkmcnt(0)
	v_pk_add_f32 v[40:41], v[40:41], v[232:233]
	v_pk_add_f32 v[42:43], v[42:43], v[234:235]
	v_pk_add_f32 v[44:45], v[44:45], v[236:237]
	v_pk_add_f32 v[46:47], v[46:47], v[238:239]
	ds_read_b32 v224, v245 offset:108
	ds_read_b32 v225, v245 offset:104
	ds_read_b32 v226, v245 offset:100
	ds_read_b32 v227, v245 offset:96
	ds_read_b32 v228, v245 offset:76
	ds_read_b32 v229, v245 offset:72
	ds_read_b32 v230, v245 offset:68
	ds_read_b32 v231, v245 offset:64
	ds_read_b32 v232, v245 offset:44
	ds_read_b32 v233, v245 offset:40
	ds_read_b32 v234, v245 offset:36
	ds_read_b32 v235, v245 offset:32
	ds_read_b32 v236, v245 offset:12
	ds_read_b32 v237, v245 offset:8
	ds_read_b32 v238, v245 offset:4
	ds_read_b32 v239, v245 offset:0
	s_waitcnt lgkmcnt(8)
	v_pk_add_f32 v[48:49], v[48:49], v[224:225]
	v_pk_add_f32 v[50:51], v[50:51], v[226:227]
	v_pk_add_f32 v[52:53], v[52:53], v[228:229]
	v_pk_add_f32 v[54:55], v[54:55], v[230:231]
	s_waitcnt lgkmcnt(0)
	v_pk_add_f32 v[56:57], v[56:57], v[232:233]
	v_pk_add_f32 v[58:59], v[58:59], v[234:235]
	v_pk_add_f32 v[60:61], v[60:61], v[236:237]
	v_pk_add_f32 v[62:63], v[62:63], v[238:239]
	s_cmp_ge_i32 s61, 2
	s_cbranch_scc1 .Lasel_softmax
; #define NEGINF (-__builtin_inff())
; DI int crow(int i, int h) { return (i & 3) + 8 * (i >> 2) + 4 * h; }
; DI void nsa_main_item(const Params& p, int b, int head, int qb, const unsigned char* blut, const float* tbl) {
;     ...
;         } else {
;           int dist[16]; float bv[16];
; #pragma unroll
;           for (int i = 0; i < 16; ++i) dist[i] = t - (kt * 32 + crow(i, h));
;           bias16(blut, tblh, dist, bv);
; #pragma unroll
;           for (int i = 0; i < 16; ++i) lg[i] = (bs && dist[i] >= 0) ? s[i] + bv[i] : NEGINF;
;         }
	v_subrev_u32_e32 v246, 32, v241
	v_cmp_le_i32_e32 vcc, 0, v241
	s_nop 1
	v_cndmask_b32_e32 v32, v199, v32, vcc
	v_cmp_le_i32_e32 vcc, 1, v241
	s_nop 1
	v_cndmask_b32_e32 v33, v199, v33, vcc
	v_cmp_le_i32_e32 vcc, 2, v241
	s_nop 1
	v_cndmask_b32_e32 v34, v199, v34, vcc
	v_cmp_le_i32_e32 vcc, 3, v241
	s_nop 1
	v_cndmask_b32_e32 v35, v199, v35, vcc
	v_cmp_le_i32_e32 vcc, 8, v241
	s_nop 1
	v_cndmask_b32_e32 v36, v199, v36, vcc
	v_cmp_le_i32_e32 vcc, 9, v241
	s_nop 1
	v_cndmask_b32_e32 v37, v199, v37, vcc
	v_cmp_le_i32_e32 vcc, 10, v241
	s_nop 1
	v_cndmask_b32_e32 v38, v199, v38, vcc
	v_cmp_le_i32_e32 vcc, 11, v241
	s_nop 1
	v_cndmask_b32_e32 v39, v199, v39, vcc
	v_cmp_le_i32_e32 vcc, 16, v241
	s_nop 1
	v_cndmask_b32_e32 v40, v199, v40, vcc
	v_cmp_le_i32_e32 vcc, 17, v241
	s_nop 1
	v_cndmask_b32_e32 v41, v199, v41, vcc
	v_cmp_le_i32_e32 vcc, 18, v241
	s_nop 1
	v_cndmask_b32_e32 v42, v199, v42, vcc
	v_cmp_le_i32_e32 vcc, 19, v241
	s_nop 1
	v_cndmask_b32_e32 v43, v199, v43, vcc
	v_cmp_le_i32_e32 vcc, 24, v241
	s_nop 1
	v_cndmask_b32_e32 v44, v199, v44, vcc
	v_cmp_le_i32_e32 vcc, 25, v241
	s_nop 1
	v_cndmask_b32_e32 v45, v199, v45, vcc
	v_cmp_le_i32_e32 vcc, 26, v241
	s_nop 1
	v_cndmask_b32_e32 v46, v199, v46, vcc
	v_cmp_le_i32_e32 vcc, 27, v241
	s_nop 1
	v_cndmask_b32_e32 v47, v199, v47, vcc
	v_cmp_le_i32_e32 vcc, 0, v246
	s_nop 1
	v_cndmask_b32_e32 v48, v199, v48, vcc
	v_cmp_le_i32_e32 vcc, 1, v246
	s_nop 1
	v_cndmask_b32_e32 v49, v199, v49, vcc
	v_cmp_le_i32_e32 vcc, 2, v246
	s_nop 1
	v_cndmask_b32_e32 v50, v199, v50, vcc
	v_cmp_le_i32_e32 vcc, 3, v246
	s_nop 1
	v_cndmask_b32_e32 v51, v199, v51, vcc
	v_cmp_le_i32_e32 vcc, 8, v246
	s_nop 1
	v_cndmask_b32_e32 v52, v199, v52, vcc
	v_cmp_le_i32_e32 vcc, 9, v246
	s_nop 1
	v_cndmask_b32_e32 v53, v199, v53, vcc
	v_cmp_le_i32_e32 vcc, 10, v246
	s_nop 1
	v_cndmask_b32_e32 v54, v199, v54, vcc
	v_cmp_le_i32_e32 vcc, 11, v246
	s_nop 1
	v_cndmask_b32_e32 v55, v199, v55, vcc
	v_cmp_le_i32_e32 vcc, 16, v246
	s_nop 1
	v_cndmask_b32_e32 v56, v199, v56, vcc
	v_cmp_le_i32_e32 vcc, 17, v246
	s_nop 1
	v_cndmask_b32_e32 v57, v199, v57, vcc
	v_cmp_le_i32_e32 vcc, 18, v246
	s_nop 1
	v_cndmask_b32_e32 v58, v199, v58, vcc
	v_cmp_le_i32_e32 vcc, 19, v246
	s_nop 1
	v_cndmask_b32_e32 v59, v199, v59, vcc
	v_cmp_le_i32_e32 vcc, 24, v246
	s_nop 1
	v_cndmask_b32_e32 v60, v199, v60, vcc
	v_cmp_le_i32_e32 vcc, 25, v246
	s_nop 1
	v_cndmask_b32_e32 v61, v199, v61, vcc
	v_cmp_le_i32_e32 vcc, 26, v246
	s_nop 1
	v_cndmask_b32_e32 v62, v199, v62, vcc
	v_cmp_le_i32_e32 vcc, 27, v246
	s_nop 1
	v_cndmask_b32_e32 v63, v199, v63, vcc
	s_branch .Lasel_softmax

; #define MFMA32(a, b, c) __builtin_amdgcn_mfma_f32_32x32x16_bf16((a), (b), (c), 0, 0, 0)
; #define NEGINF (-__builtin_inff())
; DI float shx32(float v) { const auto r = __builtin_amdgcn_permlane32_swap(__float_as_uint(v), __float_as_uint(v), false, false); return __uint_as_float((threadIdx.x & 32) ? r[0] : r[1]); }
; DI float ex2(float x) { return __builtin_amdgcn_exp2f(x); }
; DI unsigned pack2(float a, float b) { unsigned r; asm("v_cvt_pk_bf16_f32 %0, %1, %2" : "=v"(r) : "v"(a), "v"(b)); return r; }
; DI void softmax_step_r(AttnSt& st, const float (&lg)[16], const KVT& t) {
;   float mx = NEGINF;
; #pragma unroll
;   for (int i = 0; i < 16; ++i) mx = fmaxf(mx, lg[i]);
;   mx = fmaxf(mx, shx32(mx));
;   if (__ballot(mx > NEGINF) == 0ull) return;
;   const float mnew = fmaxf(st.m, mx);
;   const float muse = (mnew == NEGINF) ? 0.f : mnew;
;   const float alpha = ex2(st.m - muse);
;   float pr[16]; float rs = 0.f;
; #pragma unroll
;   for (int i = 0; i < 16; ++i) { pr[i] = ex2(lg[i] - muse); rs += pr[i]; }
;   st.l = st.l * alpha + rs;
;   if (__ballot(mnew != st.m) != 0ull) {
; #pragma unroll
;     for (int i = 0; i < 16; ++i) { st.o0[i] *= alpha; st.o1[i] *= alpha; }
;   }
;   st.m = mnew;
; #pragma unroll
;   for (int s2 = 0; s2 < 2; ++s2) {
;     u32x4 pk; pk.x = pack2(pr[8 * s2], pr[8 * s2 + 1]); pk.y = pack2(pr[8 * s2 + 2], pr[8 * s2 + 3]); pk.z = pack2(pr[8 * s2 + 4], pr[8 * s2 + 5]); pk.w = pack2(pr[8 * s2 + 6], pr[8 * s2 + 7]);
;     const bf16x8 pb = __builtin_bit_cast(bf16x8, pk);
;     const bf16x8 va0 = __builtin_shufflevector(t.v[s2 * 4 + 0], t.v[s2 * 4 + 1], 0, 1, 2, 3, 4, 5, 6, 7);
;     st.o0 = MFMA32(va0, pb, st.o0);
;     const bf16x8 va1 = __builtin_shufflevector(t.v[s2 * 4 + 2], t.v[s2 * 4 + 3], 0, 1, 2, 3, 4, 5, 6, 7);
;     st.o1 = MFMA32(va1, pb, st.o1);
.Lasel_softmax:
	v_max3_f32 v224, v32, v33, v34
	v_max3_f32 v225, v40, v41, v42
	v_max3_f32 v226, v48, v49, v50
	v_max3_f32 v227, v56, v57, v58
	v_max3_f32 v224, v224, v35, v36
	v_max3_f32 v225, v225, v43, v44
	v_max3_f32 v226, v226, v51, v52
	v_max3_f32 v227, v227, v59, v60
	v_max3_f32 v224, v224, v37, v38
	v_max3_f32 v225, v225, v45, v46
	v_max3_f32 v226, v226, v53, v54
	v_max3_f32 v227, v227, v61, v62
	v_max_f32_e32 v224, v224, v39
	v_max_f32_e32 v225, v225, v47
	v_max_f32_e32 v226, v226, v55
	v_max_f32_e32 v227, v227, v63
	v_max3_f32 v224, v224, v225, v226
	v_max_f32_e32 v224, v224, v227
	v_mov_b32_e32 v225, v224
	v_mov_b32_e32 v226, v224
	s_nop 1
	v_permlane32_swap_b32_e32 v225, v226
	v_cndmask_b32_e64 v225, v225, v226, s[12:13]
	v_max_f32_e32 v224, v224, v225
	v_cndmask_b32_e64 v224, v199, v224, s[62:63]
	v_max_f32_e32 v225, v223, v224
	v_cmp_neq_f32_e32 vcc, v199, v225
	s_nop 1
	v_cndmask_b32_e32 v226, 0, v225, vcc
	v_sub_f32_e32 v227, v223, v226
	v_exp_f32_e32 v227, v227
	v_cndmask_b32_e64 v226, v243, v226, s[62:63]
	v_cmp_neq_f32_e32 vcc, v223, v225
	v_mov_b32_e32 v223, v225
	v_pk_add_f32 v[32:33], v[32:33], v[226:227] op_sel_hi:[1,0] neg_lo:[0,1] neg_hi:[0,1]
	v_pk_add_f32 v[34:35], v[34:35], v[226:227] op_sel_hi:[1,0] neg_lo:[0,1] neg_hi:[0,1]
	v_pk_add_f32 v[36:37], v[36:37], v[226:227] op_sel_hi:[1,0] neg_lo:[0,1] neg_hi:[0,1]
	v_pk_add_f32 v[38:39], v[38:39], v[226:227] op_sel_hi:[1,0] neg_lo:[0,1] neg_hi:[0,1]
	v_pk_add_f32 v[40:41], v[40:41], v[226:227] op_sel_hi:[1,0] neg_lo:[0,1] neg_hi:[0,1]
	v_pk_add_f32 v[42:43], v[42:43], v[226:227] op_sel_hi:[1,0] neg_lo:[0,1] neg_hi:[0,1]
	v_pk_add_f32 v[44:45], v[44:45], v[226:227] op_sel_hi:[1,0] neg_lo:[0,1] neg_hi:[0,1]
	v_pk_add_f32 v[46:47], v[46:47], v[226:227] op_sel_hi:[1,0] neg_lo:[0,1] neg_hi:[0,1]
	v_pk_add_f32 v[48:49], v[48:49], v[226:227] op_sel_hi:[1,0] neg_lo:[0,1] neg_hi:[0,1]
	v_pk_add_f32 v[50:51], v[50:51], v[226:227] op_sel_hi:[1,0] neg_lo:[0,1] neg_hi:[0,1]
	v_pk_add_f32 v[52:53], v[52:53], v[226:227] op_sel_hi:[1,0] neg_lo:[0,1] neg_hi:[0,1]
	v_pk_add_f32 v[54:55], v[54:55], v[226:227] op_sel_hi:[1,0] neg_lo:[0,1] neg_hi:[0,1]
	v_pk_add_f32 v[56:57], v[56:57], v[226:227] op_sel_hi:[1,0] neg_lo:[0,1] neg_hi:[0,1]
	v_pk_add_f32 v[58:59], v[58:59], v[226:227] op_sel_hi:[1,0] neg_lo:[0,1] neg_hi:[0,1]
	v_pk_add_f32 v[60:61], v[60:61], v[226:227] op_sel_hi:[1,0] neg_lo:[0,1] neg_hi:[0,1]
	v_pk_add_f32 v[62:63], v[62:63], v[226:227] op_sel_hi:[1,0] neg_lo:[0,1] neg_hi:[0,1]
	v_exp_f32_e32 v32, v32
	v_exp_f32_e32 v33, v33
	v_exp_f32_e32 v34, v34
	v_exp_f32_e32 v35, v35
	v_exp_f32_e32 v36, v36
	v_exp_f32_e32 v37, v37
	v_exp_f32_e32 v38, v38
	v_exp_f32_e32 v39, v39
	v_exp_f32_e32 v40, v40
	v_exp_f32_e32 v41, v41
	v_exp_f32_e32 v42, v42
	v_exp_f32_e32 v43, v43
	v_exp_f32_e32 v44, v44
	v_exp_f32_e32 v45, v45
	v_exp_f32_e32 v46, v46
	v_exp_f32_e32 v47, v47
	v_exp_f32_e32 v48, v48
	v_exp_f32_e32 v49, v49
	v_exp_f32_e32 v50, v50
	v_exp_f32_e32 v51, v51
	v_exp_f32_e32 v52, v52
	v_exp_f32_e32 v53, v53
	v_exp_f32_e32 v54, v54
	v_exp_f32_e32 v55, v55
	v_exp_f32_e32 v56, v56
	v_exp_f32_e32 v57, v57
	v_exp_f32_e32 v58, v58
	v_exp_f32_e32 v59, v59
	v_exp_f32_e32 v60, v60
	v_exp_f32_e32 v61, v61
	v_exp_f32_e32 v62, v62
	v_exp_f32_e32 v63, v63
	v_pk_add_f32 v[228:229], v[32:33], v[34:35]
	v_pk_add_f32 v[230:231], v[36:37], v[38:39]
	v_pk_add_f32 v[228:229], v[228:229], v[40:41]
	v_pk_add_f32 v[230:231], v[230:231], v[42:43]
	v_pk_add_f32 v[228:229], v[228:229], v[44:45]
	v_pk_add_f32 v[230:231], v[230:231], v[46:47]
	v_pk_add_f32 v[228:229], v[228:229], v[48:49]
	v_pk_add_f32 v[230:231], v[230:231], v[50:51]
	v_pk_add_f32 v[228:229], v[228:229], v[52:53]
	v_pk_add_f32 v[230:231], v[230:231], v[54:55]
	v_pk_add_f32 v[228:229], v[228:229], v[56:57]
	v_pk_add_f32 v[230:231], v[230:231], v[58:59]
	v_pk_add_f32 v[228:229], v[228:229], v[60:61]
	v_pk_add_f32 v[230:231], v[230:231], v[62:63]
	v_pk_add_f32 v[228:229], v[228:229], v[230:231]
	v_add_f32_e32 v228, v228, v229
	v_fma_f32 v222, v222, v227, v228
	s_cbranch_vccz .Lasel_noscale
	v_pk_mul_f32 v[0:1], v[0:1], v[226:227] op_sel:[0,1] op_sel_hi:[1,1]
	v_pk_mul_f32 v[2:3], v[2:3], v[226:227] op_sel:[0,1] op_sel_hi:[1,1]
	v_pk_mul_f32 v[4:5], v[4:5], v[226:227] op_sel:[0,1] op_sel_hi:[1,1]
	v_pk_mul_f32 v[6:7], v[6:7], v[226:227] op_sel:[0,1] op_sel_hi:[1,1]
	v_pk_mul_f32 v[8:9], v[8:9], v[226:227] op_sel:[0,1] op_sel_hi:[1,1]
	v_pk_mul_f32 v[10:11], v[10:11], v[226:227] op_sel:[0,1] op_sel_hi:[1,1]
	v_pk_mul_f32 v[12:13], v[12:13], v[226:227] op_sel:[0,1] op_sel_hi:[1,1]
	v_pk_mul_f32 v[14:15], v[14:15], v[226:227] op_sel:[0,1] op_sel_hi:[1,1]
	v_pk_mul_f32 v[16:17], v[16:17], v[226:227] op_sel:[0,1] op_sel_hi:[1,1]
	v_pk_mul_f32 v[18:19], v[18:19], v[226:227] op_sel:[0,1] op_sel_hi:[1,1]
	v_pk_mul_f32 v[20:21], v[20:21], v[226:227] op_sel:[0,1] op_sel_hi:[1,1]
	v_pk_mul_f32 v[22:23], v[22:23], v[226:227] op_sel:[0,1] op_sel_hi:[1,1]
	v_pk_mul_f32 v[24:25], v[24:25], v[226:227] op_sel:[0,1] op_sel_hi:[1,1]
	v_pk_mul_f32 v[26:27], v[26:27], v[226:227] op_sel:[0,1] op_sel_hi:[1,1]
	v_pk_mul_f32 v[28:29], v[28:29], v[226:227] op_sel:[0,1] op_sel_hi:[1,1]
	v_pk_mul_f32 v[30:31], v[30:31], v[226:227] op_sel:[0,1] op_sel_hi:[1,1]

; #define MFMA32(a, b, c) __builtin_amdgcn_mfma_f32_32x32x16_bf16((a), (b), (c), 0, 0, 0)
; #define NEGINF (-__builtin_inff())
; DI int crow(int i, int h) { return (i & 3) + 8 * (i >> 2) + 4 * h; }
; template <class KP, class VP, class ACT, class FILL>
; DI void attn_loop(AttnSt& st, const bf16x8 (&qf)[4], int k0, int k1, size_t vstride, KP kp, VP vp, ACT act, FILL fill) {
;     ...
;   for (int kt = k0; kt <= k1; ++kt) {
;     const int kn = (kt < k1) ? kt + 1 : k1;
;     const int kn2 = (kt + 2 <= k1) ? kt + 2 : k1;
;     {
;       const bf16_t* v0 = vp(kn);
; #pragma unroll
;       for (int j = 0; j < 8; ++j) nxt.v[j] = *(const s16x4*)(v0 + 256 * j);
;     }
;     bf16x8 k2[4];
;     {
;       const bf16_t* krow = kp(kn2);
; #pragma unroll
;       for (int ss = 0; ss < 4; ++ss) k2[ss] = *(const bf16x8*)(krow + 512 * ss);
;     }
;     f32x16 s_next;
; #pragma unroll
;     for (int i = 0; i < 16; ++i) s_next[i] = 0.f;
; #pragma unroll
;     for (int ss = 0; ss < 4; ++ss) s_next = MFMA32(nxt.k[ss], qf[ss], s_next);
;     if (act(kt)) {
;       float lg[16];
;       fill(kt, s_cur, lg);
;       softmax_step_r(st, lg, cur);
;     }
; DI void moba_item(const Params& p, int b, int hd, int qb, const unsigned char* blut, const float* tbl) {
;     ...
;   attn_loop(st, qf, 0, qb, 32,
;     [&](int kt) { return K + (size_t)kt * 2048 + (h * 32 + r) * 8; },
;     [&](int kt) { return Vt + (size_t)kt * 2048 + (h * 32 + r) * 4; },
;     [&](int kt) { return __ballot((mmask >> (kt >> 3)) & 1u) != 0ull; },
;     [&](int kt, const f32x16& s, float (&lg)[16]) {
;       const bool bs = (mmask >> (kt >> 3)) & 1u;
;       if (qb * 32 - (kt * 32 + 31) >= 1513) {
;         const float b31 = tblh[31];
; #pragma unroll
;         for (int i = 0; i < 16; ++i) lg[i] = bs ? s[i] + b31 : NEGINF;
;       } else {
;         int dist[16]; float bv[16];
; #pragma unroll
;         for (int i = 0; i < 16; ++i) dist[i] = t - (kt * 32 + crow(i, h));
;         bias16(blut, tblh, dist, bv);
; #pragma unroll
;         for (int i = 0; i < 16; ++i) lg[i] = (bs && dist[i] >= 0) ? s[i] + bv[i] : NEGINF;
;       }
;     });
.Lamoba_loop:
	s_waitcnt vmcnt(2)
	s_barrier
	s_lshr_b32 s23, s56, 1
	s_add_u32 s23, s23, 2
	s_sub_u32 s61, s100, 0x4000
	s_cmp_lt_u32 s61, 0x10000
	s_cselect_b32 s61, 0x18000, s61
	s_lshr_b32 s24, s59, 1
	s_min_u32 s24, s23, s24
	s_lshl_b32 s26, s24, 13
	s_lshl_b32 s24, s58, 10
	s_add_u32 s26, s26, s24
	s_mov_b32 s27, 0
	v_lshl_add_u64 v[186:187], v[134:135], 0, s[26:27]
	v_lshl_add_u64 v[218:219], v[136:137], 0, s[26:27]
	v_add_co_u32_e32 v218, vcc, v218, v185
	v_addc_co_u32_e32 v219, vcc, 0, v219, vcc
	s_add_u32 s24, s24, s61
	s_mov_b32 m0, s24
	s_nop 0
	global_load_lds_dwordx4 v[186:187], off
	s_add_u32 s24, s24, 0x2000
	s_mov_b32 m0, s24
	s_nop 0
	global_load_lds_dwordx4 v[218:219], off
	s_cmp_le_u32 s56, s60
	s_cbranch_scc0 .Lamoba_skip
	v_lshl_add_u32 v186, v185, 1, s100
	ds_read_b128 v[96:99], v186 offset:0
	ds_read_b128 v[100:103], v186 offset:1024
	ds_read_b128 v[104:107], v186 offset:2048
	ds_read_b128 v[108:111], v186 offset:3072
	ds_read_b128 v[112:115], v186 offset:4096
	ds_read_b128 v[116:119], v186 offset:5120
	ds_read_b128 v[120:123], v186 offset:6144
	ds_read_b128 v[124:127], v186 offset:7168
	s_sub_i32 s61, s60, s56
	s_lshr_b32 s23, s56, 3
	v_bfe_u32 v184, v157, s23, 1
	v_cmp_eq_u32_e64 s[62:63], 1, v184
	s_waitcnt lgkmcnt(0)
	v_mfma_f32_32x32x16_bf16 v[32:47], v[96:99], v[80:83], 0
	v_mfma_f32_32x32x16_bf16 v[48:63], v[112:115], v[80:83], 0
	v_mfma_f32_32x32x16_bf16 v[32:47], v[100:103], v[84:87], v[32:47]
	v_mfma_f32_32x32x16_bf16 v[48:63], v[116:119], v[84:87], v[48:63]
	v_mfma_f32_32x32x16_bf16 v[32:47], v[104:107], v[88:91], v[32:47]
	v_mfma_f32_32x32x16_bf16 v[48:63], v[120:123], v[88:91], v[48:63]
	v_mfma_f32_32x32x16_bf16 v[32:47], v[108:111], v[92:95], v[32:47]
	v_mfma_f32_32x32x16_bf16 v[48:63], v[124:127], v[92:95], v[48:63]
	v_add_u32_e32 v218, s100, v185
	ds_read_b64 v[64:65], v218 offset:8192
	ds_read_b64 v[66:67], v218 offset:8704
	ds_read_b64 v[68:69], v218 offset:9216
	ds_read_b64 v[70:71], v218 offset:9728
	ds_read_b64 v[72:73], v218 offset:10240
	ds_read_b64 v[74:75], v218 offset:10752
	ds_read_b64 v[76:77], v218 offset:11264
	ds_read_b64 v[78:79], v218 offset:11776
	ds_read_b64 v[138:139], v218 offset:12288
	ds_read_b64 v[140:141], v218 offset:12800
	ds_read_b64 v[142:143], v218 offset:13312
	ds_read_b64 v[144:145], v218 offset:13824
	ds_read_b64 v[146:147], v218 offset:14336
	ds_read_b64 v[148:149], v218 offset:14848
	ds_read_b64 v[150:151], v218 offset:15360
	ds_read_b64 v[152:153], v218 offset:15872
	s_cmp_ge_i32 s61, 50
	s_cbranch_scc1 .Lamoba_far
	s_lshl_b32 s23, s61, 5
	v_add_u32_e32 v179, s23, v158
	v_lshl_add_u32 v182, v179, 2, v180
	v_subrev_u32_e32 v183, 128, v182
	ds_read_b32 v162, v182 offset:108
	ds_read_b32 v163, v182 offset:104
	ds_read_b32 v164, v182 offset:100
	ds_read_b32 v165, v182 offset:96
	ds_read_b32 v166, v182 offset:76
	ds_read_b32 v167, v182 offset:72
	ds_read_b32 v168, v182 offset:68
	ds_read_b32 v169, v182 offset:64
	ds_read_b32 v170, v182 offset:44
	ds_read_b32 v171, v182 offset:40
	ds_read_b32 v172, v182 offset:36
	ds_read_b32 v173, v182 offset:32
	ds_read_b32 v174, v182 offset:12
	ds_read_b32 v175, v182 offset:8
	ds_read_b32 v176, v182 offset:4
	ds_read_b32 v177, v182 offset:0
	s_waitcnt lgkmcnt(8)
	v_pk_add_f32 v[32:33], v[32:33], v[162:163]
	v_pk_add_f32 v[34:35], v[34:35], v[164:165]
	v_pk_add_f32 v[36:37], v[36:37], v[166:167]
	v_pk_add_f32 v[38:39], v[38:39], v[168:169]
	s_waitcnt lgkmcnt(0)
	v_pk_add_f32 v[40:41], v[40:41], v[170:171]
	v_pk_add_f32 v[42:43], v[42:43], v[172:173]
	v_pk_add_f32 v[44:45], v[44:45], v[174:175]
	v_pk_add_f32 v[46:47], v[46:47], v[176:177]
	ds_read_b32 v162, v183 offset:108
	ds_read_b32 v163, v183 offset:104
	ds_read_b32 v164, v183 offset:100
	ds_read_b32 v165, v183 offset:96
	ds_read_b32 v166, v183 offset:76
	ds_read_b32 v167, v183 offset:72
	ds_read_b32 v168, v183 offset:68
	ds_read_b32 v169, v183 offset:64
	ds_read_b32 v170, v183 offset:44
	ds_read_b32 v171, v183 offset:40
	ds_read_b32 v172, v183 offset:36
	ds_read_b32 v173, v183 offset:32
	ds_read_b32 v174, v183 offset:12
	ds_read_b32 v175, v183 offset:8
	ds_read_b32 v176, v183 offset:4
	ds_read_b32 v177, v183 offset:0
	s_waitcnt lgkmcnt(8)
	v_pk_add_f32 v[48:49], v[48:49], v[162:163]
	v_pk_add_f32 v[50:51], v[50:51], v[164:165]
	v_pk_add_f32 v[52:53], v[52:53], v[166:167]
	v_pk_add_f32 v[54:55], v[54:55], v[168:169]
	s_waitcnt lgkmcnt(0)
	v_pk_add_f32 v[56:57], v[56:57], v[170:171]
	v_pk_add_f32 v[58:59], v[58:59], v[172:173]
	v_pk_add_f32 v[60:61], v[60:61], v[174:175]
	v_pk_add_f32 v[62:63], v[62:63], v[176:177]
	s_cmp_ge_i32 s61, 2
	s_cbranch_scc1 .Lamoba_softmax
; #define NEGINF (-__builtin_inff())
; DI int crow(int i, int h) { return (i & 3) + 8 * (i >> 2) + 4 * h; }
; DI void moba_item(const Params& p, int b, int hd, int qb, const unsigned char* blut, const float* tbl) {
;     ...
;     [&](int kt, const f32x16& s, float (&lg)[16]) {
;       const bool bs = (mmask >> (kt >> 3)) & 1u;
;       if (qb * 32 - (kt * 32 + 31) >= 1513) {
;         const float b31 = tblh[31];
; #pragma unroll
;         for (int i = 0; i < 16; ++i) lg[i] = bs ? s[i] + b31 : NEGINF;
;       } else {
;         int dist[16]; float bv[16];
; #pragma unroll
;         for (int i = 0; i < 16; ++i) dist[i] = t - (kt * 32 + crow(i, h));
;         bias16(blut, tblh, dist, bv);
; #pragma unroll
;         for (int i = 0; i < 16; ++i) lg[i] = (bs && dist[i] >= 0) ? s[i] + bv[i] : NEGINF;
;       }
;     });
	v_subrev_u32_e32 v184, 32, v179
	v_cmp_le_i32_e32 vcc, 0, v179
	s_nop 1
	v_cndmask_b32_e32 v32, v199, v32, vcc
	v_cmp_le_i32_e32 vcc, 1, v179
	s_nop 1
	v_cndmask_b32_e32 v33, v199, v33, vcc
	v_cmp_le_i32_e32 vcc, 2, v179
	s_nop 1
	v_cndmask_b32_e32 v34, v199, v34, vcc
	v_cmp_le_i32_e32 vcc, 3, v179
	s_nop 1
	v_cndmask_b32_e32 v35, v199, v35, vcc
	v_cmp_le_i32_e32 vcc, 8, v179
	s_nop 1
	v_cndmask_b32_e32 v36, v199, v36, vcc
	v_cmp_le_i32_e32 vcc, 9, v179
	s_nop 1
	v_cndmask_b32_e32 v37, v199, v37, vcc
	v_cmp_le_i32_e32 vcc, 10, v179
	s_nop 1
	v_cndmask_b32_e32 v38, v199, v38, vcc
	v_cmp_le_i32_e32 vcc, 11, v179
	s_nop 1
	v_cndmask_b32_e32 v39, v199, v39, vcc
	v_cmp_le_i32_e32 vcc, 16, v179
	s_nop 1
	v_cndmask_b32_e32 v40, v199, v40, vcc
	v_cmp_le_i32_e32 vcc, 17, v179
	s_nop 1
	v_cndmask_b32_e32 v41, v199, v41, vcc
	v_cmp_le_i32_e32 vcc, 18, v179
	s_nop 1
	v_cndmask_b32_e32 v42, v199, v42, vcc
	v_cmp_le_i32_e32 vcc, 19, v179
	s_nop 1
	v_cndmask_b32_e32 v43, v199, v43, vcc
	v_cmp_le_i32_e32 vcc, 24, v179
	s_nop 1
	v_cndmask_b32_e32 v44, v199, v44, vcc
	v_cmp_le_i32_e32 vcc, 25, v179
	s_nop 1
	v_cndmask_b32_e32 v45, v199, v45, vcc
	v_cmp_le_i32_e32 vcc, 26, v179
	s_nop 1
	v_cndmask_b32_e32 v46, v199, v46, vcc
	v_cmp_le_i32_e32 vcc, 27, v179
	s_nop 1
	v_cndmask_b32_e32 v47, v199, v47, vcc
	v_cmp_le_i32_e32 vcc, 0, v184
	s_nop 1
	v_cndmask_b32_e32 v48, v199, v48, vcc
	v_cmp_le_i32_e32 vcc, 1, v184
	s_nop 1
	v_cndmask_b32_e32 v49, v199, v49, vcc
	v_cmp_le_i32_e32 vcc, 2, v184
	s_nop 1
	v_cndmask_b32_e32 v50, v199, v50, vcc
	v_cmp_le_i32_e32 vcc, 3, v184
	s_nop 1
	v_cndmask_b32_e32 v51, v199, v51, vcc
	v_cmp_le_i32_e32 vcc, 8, v184
	s_nop 1
	v_cndmask_b32_e32 v52, v199, v52, vcc
	v_cmp_le_i32_e32 vcc, 9, v184
	s_nop 1
	v_cndmask_b32_e32 v53, v199, v53, vcc
	v_cmp_le_i32_e32 vcc, 10, v184
	s_nop 1
	v_cndmask_b32_e32 v54, v199, v54, vcc
	v_cmp_le_i32_e32 vcc, 11, v184
	s_nop 1
	v_cndmask_b32_e32 v55, v199, v55, vcc
	v_cmp_le_i32_e32 vcc, 16, v184
	s_nop 1
	v_cndmask_b32_e32 v56, v199, v56, vcc
	v_cmp_le_i32_e32 vcc, 17, v184
	s_nop 1
	v_cndmask_b32_e32 v57, v199, v57, vcc
	v_cmp_le_i32_e32 vcc, 18, v184
	s_nop 1
	v_cndmask_b32_e32 v58, v199, v58, vcc
	v_cmp_le_i32_e32 vcc, 19, v184
	s_nop 1
	v_cndmask_b32_e32 v59, v199, v59, vcc
	v_cmp_le_i32_e32 vcc, 24, v184
	s_nop 1
	v_cndmask_b32_e32 v60, v199, v60, vcc
	v_cmp_le_i32_e32 vcc, 25, v184
	s_nop 1
	v_cndmask_b32_e32 v61, v199, v61, vcc
	v_cmp_le_i32_e32 vcc, 26, v184
	s_nop 1
	v_cndmask_b32_e32 v62, v199, v62, vcc
	v_cmp_le_i32_e32 vcc, 27, v184
	s_nop 1
	v_cndmask_b32_e32 v63, v199, v63, vcc
	s_branch .Lamoba_softmax
.Lamoba_far:
	s_nop 7
	v_pk_add_f32 v[32:33], v[32:33], v[178:179] op_sel_hi:[1,0]
	v_pk_add_f32 v[34:35], v[34:35], v[178:179] op_sel_hi:[1,0]
	v_pk_add_f32 v[36:37], v[36:37], v[178:179] op_sel_hi:[1,0]
	v_pk_add_f32 v[38:39], v[38:39], v[178:179] op_sel_hi:[1,0]
	v_pk_add_f32 v[40:41], v[40:41], v[178:179] op_sel_hi:[1,0]
	v_pk_add_f32 v[42:43], v[42:43], v[178:179] op_sel_hi:[1,0]
	v_pk_add_f32 v[44:45], v[44:45], v[178:179] op_sel_hi:[1,0]
	v_pk_add_f32 v[46:47], v[46:47], v[178:179] op_sel_hi:[1,0]
	v_pk_add_f32 v[48:49], v[48:49], v[178:179] op_sel_hi:[1,0]
	v_pk_add_f32 v[50:51], v[50:51], v[178:179] op_sel_hi:[1,0]
	v_pk_add_f32 v[52:53], v[52:53], v[178:179] op_sel_hi:[1,0]
	v_pk_add_f32 v[54:55], v[54:55], v[178:179] op_sel_hi:[1,0]
	v_pk_add_f32 v[56:57], v[56:57], v[178:179] op_sel_hi:[1,0]
	v_pk_add_f32 v[58:59], v[58:59], v[178:179] op_sel_hi:[1,0]
	v_pk_add_f32 v[60:61], v[60:61], v[178:179] op_sel_hi:[1,0]
	v_pk_add_f32 v[62:63], v[62:63], v[178:179] op_sel_hi:[1,0]
; #define MFMA32(a, b, c) __builtin_amdgcn_mfma_f32_32x32x16_bf16((a), (b), (c), 0, 0, 0)
; #define NEGINF (-__builtin_inff())
; DI float shx32(float v) { const auto r = __builtin_amdgcn_permlane32_swap(__float_as_uint(v), __float_as_uint(v), false, false); return __uint_as_float((threadIdx.x & 32) ? r[0] : r[1]); }
; DI float ex2(float x) { return __builtin_amdgcn_exp2f(x); }
; DI unsigned pack2(float a, float b) { unsigned r; asm("v_cvt_pk_bf16_f32 %0, %1, %2" : "=v"(r) : "v"(a), "v"(b)); return r; }
; DI void softmax_step_r(AttnSt& st, const float (&lg)[16], const KVT& t) {
;   float mx = NEGINF;
; #pragma unroll
;   for (int i = 0; i < 16; ++i) mx = fmaxf(mx, lg[i]);
;   mx = fmaxf(mx, shx32(mx));
;   if (__ballot(mx > NEGINF) == 0ull) return;
;   const float mnew = fmaxf(st.m, mx);
;   const float muse = (mnew == NEGINF) ? 0.f : mnew;
;   const float alpha = ex2(st.m - muse);
;   float pr[16]; float rs = 0.f;
; #pragma unroll
;   for (int i = 0; i < 16; ++i) { pr[i] = ex2(lg[i] - muse); rs += pr[i]; }
;   st.l = st.l * alpha + rs;
;   if (__ballot(mnew != st.m) != 0ull) {
; #pragma unroll
;     for (int i = 0; i < 16; ++i) { st.o0[i] *= alpha; st.o1[i] *= alpha; }
;   }
;   st.m = mnew;
; #pragma unroll
;   for (int s2 = 0; s2 < 2; ++s2) {
;     u32x4 pk; pk.x = pack2(pr[8 * s2], pr[8 * s2 + 1]); pk.y = pack2(pr[8 * s2 + 2], pr[8 * s2 + 3]); pk.z = pack2(pr[8 * s2 + 4], pr[8 * s2 + 5]); pk.w = pack2(pr[8 * s2 + 6], pr[8 * s2 + 7]);
;     const bf16x8 pb = __builtin_bit_cast(bf16x8, pk);
;     const bf16x8 va0 = __builtin_shufflevector(t.v[s2 * 4 + 0], t.v[s2 * 4 + 1], 0, 1, 2, 3, 4, 5, 6, 7);
;     st.o0 = MFMA32(va0, pb, st.o0);
;     const bf16x8 va1 = __builtin_shufflevector(t.v[s2 * 4 + 2], t.v[s2 * 4 + 3], 0, 1, 2, 3, 4, 5, 6, 7);
;     st.o1 = MFMA32(va1, pb, st.o1);
.Lamoba_softmax:
	v_max3_f32 v162, v32, v33, v34
	v_max3_f32 v163, v40, v41, v42
	v_max3_f32 v164, v48, v49, v50
	v_max3_f32 v165, v56, v57, v58
	v_max3_f32 v162, v162, v35, v36
	v_max3_f32 v163, v163, v43, v44
	v_max3_f32 v164, v164, v51, v52
	v_max3_f32 v165, v165, v59, v60
	v_max3_f32 v162, v162, v37, v38
	v_max3_f32 v163, v163, v45, v46
	v_max3_f32 v164, v164, v53, v54
	v_max3_f32 v165, v165, v61, v62
	v_max_f32_e32 v162, v162, v39
	v_max_f32_e32 v163, v163, v47
	v_max_f32_e32 v164, v164, v55
	v_max_f32_e32 v165, v165, v63
	v_max3_f32 v162, v162, v163, v164
	v_max_f32_e32 v162, v162, v165
	v_mov_b32_e32 v163, v162
	v_mov_b32_e32 v164, v162
	s_nop 1
	v_permlane32_swap_b32_e32 v163, v164
	v_cndmask_b32_e64 v163, v163, v164, s[12:13]
	v_max_f32_e32 v162, v162, v163
	v_cndmask_b32_e64 v162, v199, v162, s[62:63]
	v_max_f32_e32 v163, v161, v162
	v_cmp_neq_f32_e32 vcc, v199, v163
	s_nop 1
	v_cndmask_b32_e32 v164, 0, v163, vcc
	v_sub_f32_e32 v165, v161, v164
	v_exp_f32_e32 v165, v165
	v_cndmask_b32_e64 v164, v181, v164, s[62:63]
	v_cmp_neq_f32_e32 vcc, v161, v163
	v_mov_b32_e32 v161, v163
	v_pk_add_f32 v[32:33], v[32:33], v[164:165] op_sel_hi:[1,0] neg_lo:[0,1] neg_hi:[0,1]
	v_pk_add_f32 v[34:35], v[34:35], v[164:165] op_sel_hi:[1,0] neg_lo:[0,1] neg_hi:[0,1]
	v_pk_add_f32 v[36:37], v[36:37], v[164:165] op_sel_hi:[1,0] neg_lo:[0,1] neg_hi:[0,1]
	v_pk_add_f32 v[38:39], v[38:39], v[164:165] op_sel_hi:[1,0] neg_lo:[0,1] neg_hi:[0,1]
	v_pk_add_f32 v[40:41], v[40:41], v[164:165] op_sel_hi:[1,0] neg_lo:[0,1] neg_hi:[0,1]
	v_pk_add_f32 v[42:43], v[42:43], v[164:165] op_sel_hi:[1,0] neg_lo:[0,1] neg_hi:[0,1]
	v_pk_add_f32 v[44:45], v[44:45], v[164:165] op_sel_hi:[1,0] neg_lo:[0,1] neg_hi:[0,1]
	v_pk_add_f32 v[46:47], v[46:47], v[164:165] op_sel_hi:[1,0] neg_lo:[0,1] neg_hi:[0,1]
	v_pk_add_f32 v[48:49], v[48:49], v[164:165] op_sel_hi:[1,0] neg_lo:[0,1] neg_hi:[0,1]
	v_pk_add_f32 v[50:51], v[50:51], v[164:165] op_sel_hi:[1,0] neg_lo:[0,1] neg_hi:[0,1]
	v_pk_add_f32 v[52:53], v[52:53], v[164:165] op_sel_hi:[1,0] neg_lo:[0,1] neg_hi:[0,1]
	v_pk_add_f32 v[54:55], v[54:55], v[164:165] op_sel_hi:[1,0] neg_lo:[0,1] neg_hi:[0,1]
	v_pk_add_f32 v[56:57], v[56:57], v[164:165] op_sel_hi:[1,0] neg_lo:[0,1] neg_hi:[0,1]
	v_pk_add_f32 v[58:59], v[58:59], v[164:165] op_sel_hi:[1,0] neg_lo:[0,1] neg_hi:[0,1]
	v_pk_add_f32 v[60:61], v[60:61], v[164:165] op_sel_hi:[1,0] neg_lo:[0,1] neg_hi:[0,1]
	v_pk_add_f32 v[62:63], v[62:63], v[164:165] op_sel_hi:[1,0] neg_lo:[0,1] neg_hi:[0,1]
	v_exp_f32_e32 v32, v32
	v_exp_f32_e32 v33, v33
	v_exp_f32_e32 v34, v34
	v_exp_f32_e32 v35, v35
	v_exp_f32_e32 v36, v36
	v_exp_f32_e32 v37, v37
	v_exp_f32_e32 v38, v38
	v_exp_f32_e32 v39, v39
	v_exp_f32_e32 v40, v40
	v_exp_f32_e32 v41, v41
	v_exp_f32_e32 v42, v42
	v_exp_f32_e32 v43, v43
	v_exp_f32_e32 v44, v44
	v_exp_f32_e32 v45, v45
	v_exp_f32_e32 v46, v46
	v_exp_f32_e32 v47, v47
	v_exp_f32_e32 v48, v48
	v_exp_f32_e32 v49, v49
	v_exp_f32_e32 v50, v50
	v_exp_f32_e32 v51, v51
	v_exp_f32_e32 v52, v52
	v_exp_f32_e32 v53, v53
	v_exp_f32_e32 v54, v54
	v_exp_f32_e32 v55, v55
	v_exp_f32_e32 v56, v56
	v_exp_f32_e32 v57, v57
	v_exp_f32_e32 v58, v58
	v_exp_f32_e32 v59, v59
	v_exp_f32_e32 v60, v60
	v_exp_f32_e32 v61, v61
	v_exp_f32_e32 v62, v62
	v_exp_f32_e32 v63, v63
	v_pk_add_f32 v[166:167], v[32:33], v[34:35]
	v_pk_add_f32 v[168:169], v[36:37], v[38:39]
	v_pk_add_f32 v[166:167], v[166:167], v[40:41]
	v_pk_add_f32 v[168:169], v[168:169], v[42:43]
	v_pk_add_f32 v[166:167], v[166:167], v[44:45]
	v_pk_add_f32 v[168:169], v[168:169], v[46:47]
	v_pk_add_f32 v[166:167], v[166:167], v[48:49]
	v_pk_add_f32 v[168:169], v[168:169], v[50:51]
	v_pk_add_f32 v[166:167], v[166:167], v[52:53]
	v_pk_add_f32 v[168:169], v[168:169], v[54:55]
	v_pk_add_f32 v[166:167], v[166:167], v[56:57]
	v_pk_add_f32 v[168:169], v[168:169], v[58:59]
	v_pk_add_f32 v[166:167], v[166:167], v[60:61]
	v_pk_add_f32 v[168:169], v[168:169], v[62:63]
	v_pk_add_f32 v[166:167], v[166:167], v[168:169]
	v_add_f32_e32 v166, v166, v167
	v_fma_f32 v160, v160, v165, v166
	s_cbranch_vccz .Lamoba_noscale
	v_pk_mul_f32 v[0:1], v[0:1], v[164:165] op_sel:[0,1] op_sel_hi:[1,1]
	v_pk_mul_f32 v[2:3], v[2:3], v[164:165] op_sel:[0,1] op_sel_hi:[1,1]
	v_pk_mul_f32 v[4:5], v[4:5], v[164:165] op_sel:[0,1] op_sel_hi:[1,1]
	v_pk_mul_f32 v[6:7], v[6:7], v[164:165] op_sel:[0,1] op_sel_hi:[1,1]
	v_pk_mul_f32 v[8:9], v[8:9], v[164:165] op_sel:[0,1] op_sel_hi:[1,1]
	v_pk_mul_f32 v[10:11], v[10:11], v[164:165] op_sel:[0,1] op_sel_hi:[1,1]
	v_pk_mul_f32 v[12:13], v[12:13], v[164:165] op_sel:[0,1] op_sel_hi:[1,1]
	v_pk_mul_f32 v[14:15], v[14:15], v[164:165] op_sel:[0,1] op_sel_hi:[1,1]
	v_pk_mul_f32 v[16:17], v[16:17], v[164:165] op_sel:[0,1] op_sel_hi:[1,1]
	v_pk_mul_f32 v[18:19], v[18:19], v[164:165] op_sel:[0,1] op_sel_hi:[1,1]
	v_pk_mul_f32 v[20:21], v[20:21], v[164:165] op_sel:[0,1] op_sel_hi:[1,1]
	v_pk_mul_f32 v[22:23], v[22:23], v[164:165] op_sel:[0,1] op_sel_hi:[1,1]
	v_pk_mul_f32 v[24:25], v[24:25], v[164:165] op_sel:[0,1] op_sel_hi:[1,1]
	v_pk_mul_f32 v[26:27], v[26:27], v[164:165] op_sel:[0,1] op_sel_hi:[1,1]
	v_pk_mul_f32 v[28:29], v[28:29], v[164:165] op_sel:[0,1] op_sel_hi:[1,1]
	v_pk_mul_f32 v[30:31], v[30:31], v[164:165] op_sel:[0,1] op_sel_hi:[1,1]

; #define MFMA32(a, b, c) __builtin_amdgcn_mfma_f32_32x32x16_bf16((a), (b), (c), 0, 0, 0)
; #define NEGINF (-__builtin_inff())
; DI int crow(int i, int h) { return (i & 3) + 8 * (i >> 2) + 4 * h; }
; template <class KP, class VP, class ACT, class FILL>
; DI void attn_loop(AttnSt& st, const bf16x8 (&qf)[4], int k0, int k1, size_t vstride, KP kp, VP vp, ACT act, FILL fill) {
;     ...
;   for (int kt = k0; kt <= k1; ++kt) {
;     const int kn = (kt < k1) ? kt + 1 : k1;
;     const int kn2 = (kt + 2 <= k1) ? kt + 2 : k1;
;     {
;       const bf16_t* v0 = vp(kn);
; #pragma unroll
;       for (int j = 0; j < 8; ++j) nxt.v[j] = *(const s16x4*)(v0 + 256 * j);
;     }
;     bf16x8 k2[4];
;     {
;       const bf16_t* krow = kp(kn2);
; #pragma unroll
;       for (int ss = 0; ss < 4; ++ss) k2[ss] = *(const bf16x8*)(krow + 512 * ss);
;     }
;     f32x16 s_next;
; #pragma unroll
;     for (int i = 0; i < 16; ++i) s_next[i] = 0.f;
; #pragma unroll
;     for (int ss = 0; ss < 4; ++ss) s_next = MFMA32(nxt.k[ss], qf[ss], s_next);
;     if (act(kt)) {
;       float lg[16];
;       fill(kt, s_cur, lg);
;       softmax_step_r(st, lg, cur);
;     }
; DI void nsa_win_item(const Params& p, int b, int head, int qb, const unsigned char* blut, const float* tbl) {
;     ...
;     attn_loop(st, qf, k0, qb, 32,
;       [&](int kt) { return K + (size_t)kt * 2048 + (h * 32 + r) * 8; },
;       [&](int kt) { return Vt + (size_t)kt * 2048 + (h * 32 + r) * 4; },
;       [&](int kt) { return true; },
;       [&](int kt, const f32x16& s, float (&lg)[16]) {
;         int dist[16]; float bv[16];
; #pragma unroll
;         for (int i = 0; i < 16; ++i) dist[i] = t - (kt * 32 + crow(i, h));
;         bias16(blut, tblh, dist, bv);
; #pragma unroll
;         for (int i = 0; i < 16; ++i) lg[i] = (dist[i] >= 0 && dist[i] < 512) ? s[i] + bv[i] : NEGINF;
;       });
.Lawin4_loop:
	s_waitcnt vmcnt(2)
	s_barrier
	s_lshr_b32 s23, s56, 1
	s_add_u32 s23, s23, 2
	s_sub_u32 s61, s64, 0x4000
	s_cmp_lt_u32 s61, 0x10000
	s_cselect_b32 s61, 0x18000, s61
	s_lshr_b32 s24, s59, 1
	s_min_u32 s24, s23, s24
	s_lshl_b32 s26, s24, 13
	s_lshl_b32 s24, s58, 10
	s_add_u32 s26, s26, s24
	s_mov_b32 s27, 0
	v_lshl_add_u64 v[186:187], v[116:117], 0, s[26:27]
	v_lshl_add_u64 v[126:127], v[114:115], 0, s[26:27]
	v_add_co_u32_e32 v126, vcc, v126, v185
	v_addc_co_u32_e32 v127, vcc, 0, v127, vcc
	s_add_u32 s24, s24, s61
	s_mov_b32 m0, s24
	s_nop 0
	global_load_lds_dwordx4 v[186:187], off
	s_add_u32 s24, s24, 0x2000
	s_mov_b32 m0, s24
	s_nop 0
	global_load_lds_dwordx4 v[126:127], off
	s_cmp_le_u32 s56, s60
	s_cbranch_scc0 .Lawin4_skip
	s_add_u32 s24, s56, 1
	s_cmp_ge_u32 s24, s65
	s_cbranch_scc0 .Lawin4_skip
	v_lshl_add_u32 v186, v185, 1, s64
	ds_read_b128 v[80:83], v186 offset:0
	ds_read_b128 v[84:87], v186 offset:1024
	ds_read_b128 v[88:91], v186 offset:2048
	ds_read_b128 v[92:95], v186 offset:3072
	ds_read_b128 v[96:99], v186 offset:4096
	ds_read_b128 v[100:103], v186 offset:5120
	ds_read_b128 v[104:107], v186 offset:6144
	ds_read_b128 v[108:111], v186 offset:7168
	s_sub_i32 s61, s60, s56
	s_waitcnt lgkmcnt(0)
	v_mfma_f32_32x32x16_bf16 v[32:47], v[80:83], v[64:67], 0
	v_mfma_f32_32x32x16_bf16 v[48:63], v[96:99], v[64:67], 0
	v_mfma_f32_32x32x16_bf16 v[32:47], v[84:87], v[68:71], v[32:47]
	v_mfma_f32_32x32x16_bf16 v[48:63], v[100:103], v[68:71], v[48:63]
	v_mfma_f32_32x32x16_bf16 v[32:47], v[88:91], v[72:75], v[32:47]
	v_mfma_f32_32x32x16_bf16 v[48:63], v[104:107], v[72:75], v[48:63]
	v_mfma_f32_32x32x16_bf16 v[32:47], v[92:95], v[76:79], v[32:47]
	v_mfma_f32_32x32x16_bf16 v[48:63], v[108:111], v[76:79], v[48:63]
	v_add_u32_e32 v126, s64, v185
	ds_read_b64 v[146:147], v126 offset:8192
	ds_read_b64 v[148:149], v126 offset:8704
	ds_read_b64 v[150:151], v126 offset:9216
	ds_read_b64 v[152:153], v126 offset:9728
	ds_read_b64 v[154:155], v126 offset:10240
	ds_read_b64 v[156:157], v126 offset:10752
	ds_read_b64 v[158:159], v126 offset:11264
	ds_read_b64 v[160:161], v126 offset:11776
	ds_read_b64 v[162:163], v126 offset:12288
	ds_read_b64 v[164:165], v126 offset:12800
	ds_read_b64 v[166:167], v126 offset:13312
	ds_read_b64 v[168:169], v126 offset:13824
	ds_read_b64 v[170:171], v126 offset:14336
	ds_read_b64 v[172:173], v126 offset:14848
	ds_read_b64 v[174:175], v126 offset:15360
	ds_read_b64 v[176:177], v126 offset:15872
	s_cmp_ge_i32 s61, 50
	s_cbranch_scc1 .Lawin4_far
	s_lshl_b32 s23, s61, 5
	v_add_u32_e32 v179, s23, v142
	v_lshl_add_u32 v182, v179, 2, v180
	v_subrev_u32_e32 v183, 128, v182
	ds_read_b32 v118, v182 offset:108
	ds_read_b32 v119, v182 offset:104
	ds_read_b32 v120, v182 offset:100
	ds_read_b32 v121, v182 offset:96
	ds_read_b32 v122, v182 offset:76
	ds_read_b32 v123, v182 offset:72
	ds_read_b32 v124, v182 offset:68
	ds_read_b32 v125, v182 offset:64
	ds_read_b32 v132, v182 offset:44
	ds_read_b32 v133, v182 offset:40
	ds_read_b32 v134, v182 offset:36
	ds_read_b32 v135, v182 offset:32
	ds_read_b32 v218, v182 offset:12
	ds_read_b32 v219, v182 offset:8
	ds_read_b32 v220, v182 offset:4
	ds_read_b32 v221, v182 offset:0
	s_waitcnt lgkmcnt(8)
	v_pk_add_f32 v[32:33], v[32:33], v[118:119]
	v_pk_add_f32 v[34:35], v[34:35], v[120:121]
	v_pk_add_f32 v[36:37], v[36:37], v[122:123]
	v_pk_add_f32 v[38:39], v[38:39], v[124:125]
	s_waitcnt lgkmcnt(0)
	v_pk_add_f32 v[40:41], v[40:41], v[132:133]
	v_pk_add_f32 v[42:43], v[42:43], v[134:135]
	v_pk_add_f32 v[44:45], v[44:45], v[218:219]
	v_pk_add_f32 v[46:47], v[46:47], v[220:221]
	ds_read_b32 v118, v183 offset:108
	ds_read_b32 v119, v183 offset:104
	ds_read_b32 v120, v183 offset:100
	ds_read_b32 v121, v183 offset:96
	ds_read_b32 v122, v183 offset:76
	ds_read_b32 v123, v183 offset:72
	ds_read_b32 v124, v183 offset:68
	ds_read_b32 v125, v183 offset:64
	ds_read_b32 v132, v183 offset:44
	ds_read_b32 v133, v183 offset:40
	ds_read_b32 v134, v183 offset:36
	ds_read_b32 v135, v183 offset:32
	ds_read_b32 v218, v183 offset:12
	ds_read_b32 v219, v183 offset:8
	ds_read_b32 v220, v183 offset:4
	ds_read_b32 v221, v183 offset:0
	s_waitcnt lgkmcnt(8)
	v_pk_add_f32 v[48:49], v[48:49], v[118:119]
	v_pk_add_f32 v[50:51], v[50:51], v[120:121]
	v_pk_add_f32 v[52:53], v[52:53], v[122:123]
	v_pk_add_f32 v[54:55], v[54:55], v[124:125]
	s_waitcnt lgkmcnt(0)
	v_pk_add_f32 v[56:57], v[56:57], v[132:133]
	v_pk_add_f32 v[58:59], v[58:59], v[134:135]
	v_pk_add_f32 v[60:61], v[60:61], v[218:219]
	v_pk_add_f32 v[62:63], v[62:63], v[220:221]
	s_cmp_ge_i32 s61, 15
	s_cbranch_scc0 .Lawin4_nowin
; #define NEGINF (-__builtin_inff())
; DI int crow(int i, int h) { return (i & 3) + 8 * (i >> 2) + 4 * h; }
; DI void nsa_win_item(const Params& p, int b, int head, int qb, const unsigned char* blut, const float* tbl) {
;     ...
;       [&](int kt, const f32x16& s, float (&lg)[16]) {
;         int dist[16]; float bv[16];
; #pragma unroll
;         for (int i = 0; i < 16; ++i) dist[i] = t - (kt * 32 + crow(i, h));
;         bias16(blut, tblh, dist, bv);
; #pragma unroll
;         for (int i = 0; i < 16; ++i) lg[i] = (dist[i] >= 0 && dist[i] < 512) ? s[i] + bv[i] : NEGINF;
;       });
	v_subrev_u32_e32 v184, 32, v179
	v_cmp_gt_i32_e32 vcc, 0x200, v179
	s_nop 1
	v_cndmask_b32_e32 v32, v199, v32, vcc
	v_cmp_gt_i32_e32 vcc, 0x201, v179
	s_nop 1
	v_cndmask_b32_e32 v33, v199, v33, vcc
	v_cmp_gt_i32_e32 vcc, 0x202, v179
	s_nop 1
	v_cndmask_b32_e32 v34, v199, v34, vcc
	v_cmp_gt_i32_e32 vcc, 0x203, v179
	s_nop 1
	v_cndmask_b32_e32 v35, v199, v35, vcc
	v_cmp_gt_i32_e32 vcc, 0x208, v179
	s_nop 1
	v_cndmask_b32_e32 v36, v199, v36, vcc
	v_cmp_gt_i32_e32 vcc, 0x209, v179
	s_nop 1
	v_cndmask_b32_e32 v37, v199, v37, vcc
	v_cmp_gt_i32_e32 vcc, 0x20a, v179
	s_nop 1
	v_cndmask_b32_e32 v38, v199, v38, vcc
	v_cmp_gt_i32_e32 vcc, 0x20b, v179
	s_nop 1
	v_cndmask_b32_e32 v39, v199, v39, vcc
	v_cmp_gt_i32_e32 vcc, 0x210, v179
	s_nop 1
	v_cndmask_b32_e32 v40, v199, v40, vcc
	v_cmp_gt_i32_e32 vcc, 0x211, v179
	s_nop 1
	v_cndmask_b32_e32 v41, v199, v41, vcc
	v_cmp_gt_i32_e32 vcc, 0x212, v179
	s_nop 1
	v_cndmask_b32_e32 v42, v199, v42, vcc
	v_cmp_gt_i32_e32 vcc, 0x213, v179
	s_nop 1
	v_cndmask_b32_e32 v43, v199, v43, vcc
	v_cmp_gt_i32_e32 vcc, 0x218, v179
	s_nop 1
	v_cndmask_b32_e32 v44, v199, v44, vcc
	v_cmp_gt_i32_e32 vcc, 0x219, v179
	s_nop 1
	v_cndmask_b32_e32 v45, v199, v45, vcc
	v_cmp_gt_i32_e32 vcc, 0x21a, v179
	s_nop 1
	v_cndmask_b32_e32 v46, v199, v46, vcc
	v_cmp_gt_i32_e32 vcc, 0x21b, v179
	s_nop 1
	v_cndmask_b32_e32 v47, v199, v47, vcc
	v_cmp_gt_i32_e32 vcc, 0x200, v184
	s_nop 1
	v_cndmask_b32_e32 v48, v199, v48, vcc
	v_cmp_gt_i32_e32 vcc, 0x201, v184
	s_nop 1
	v_cndmask_b32_e32 v49, v199, v49, vcc
	v_cmp_gt_i32_e32 vcc, 0x202, v184
	s_nop 1
	v_cndmask_b32_e32 v50, v199, v50, vcc
	v_cmp_gt_i32_e32 vcc, 0x203, v184
	s_nop 1
	v_cndmask_b32_e32 v51, v199, v51, vcc
	v_cmp_gt_i32_e32 vcc, 0x208, v184
	s_nop 1
	v_cndmask_b32_e32 v52, v199, v52, vcc
	v_cmp_gt_i32_e32 vcc, 0x209, v184
	s_nop 1
	v_cndmask_b32_e32 v53, v199, v53, vcc
	v_cmp_gt_i32_e32 vcc, 0x20a, v184
	s_nop 1
	v_cndmask_b32_e32 v54, v199, v54, vcc
	v_cmp_gt_i32_e32 vcc, 0x20b, v184
	s_nop 1
	v_cndmask_b32_e32 v55, v199, v55, vcc
	v_cmp_gt_i32_e32 vcc, 0x210, v184
	s_nop 1
	v_cndmask_b32_e32 v56, v199, v56, vcc
	v_cmp_gt_i32_e32 vcc, 0x211, v184
	s_nop 1
	v_cndmask_b32_e32 v57, v199, v57, vcc
	v_cmp_gt_i32_e32 vcc, 0x212, v184
	s_nop 1
	v_cndmask_b32_e32 v58, v199, v58, vcc
	v_cmp_gt_i32_e32 vcc, 0x213, v184
	s_nop 1
	v_cndmask_b32_e32 v59, v199, v59, vcc
	v_cmp_gt_i32_e32 vcc, 0x218, v184
	s_nop 1
	v_cndmask_b32_e32 v60, v199, v60, vcc
	v_cmp_gt_i32_e32 vcc, 0x219, v184
	s_nop 1
	v_cndmask_b32_e32 v61, v199, v61, vcc
	v_cmp_gt_i32_e32 vcc, 0x21a, v184
	s_nop 1
	v_cndmask_b32_e32 v62, v199, v62, vcc
	v_cmp_gt_i32_e32 vcc, 0x21b, v184
	s_nop 1
	v_cndmask_b32_e32 v63, v199, v63, vcc

; #define MFMA32(a, b, c) __builtin_amdgcn_mfma_f32_32x32x16_bf16((a), (b), (c), 0, 0, 0)
; #define NEGINF (-__builtin_inff())
; DI float shx32(float v) { const auto r = __builtin_amdgcn_permlane32_swap(__float_as_uint(v), __float_as_uint(v), false, false); return __uint_as_float((threadIdx.x & 32) ? r[0] : r[1]); }
; DI float ex2(float x) { return __builtin_amdgcn_exp2f(x); }
; DI unsigned pack2(float a, float b) { unsigned r; asm("v_cvt_pk_bf16_f32 %0, %1, %2" : "=v"(r) : "v"(a), "v"(b)); return r; }
; DI void softmax_step_r(AttnSt& st, const float (&lg)[16], const KVT& t) {
;   float mx = NEGINF;
; #pragma unroll
;   for (int i = 0; i < 16; ++i) mx = fmaxf(mx, lg[i]);
;   mx = fmaxf(mx, shx32(mx));
;   if (__ballot(mx > NEGINF) == 0ull) return;
;   const float mnew = fmaxf(st.m, mx);
;   const float muse = (mnew == NEGINF) ? 0.f : mnew;
;   const float alpha = ex2(st.m - muse);
;   float pr[16]; float rs = 0.f;
; #pragma unroll
;   for (int i = 0; i < 16; ++i) { pr[i] = ex2(lg[i] - muse); rs += pr[i]; }
;   st.l = st.l * alpha + rs;
;   if (__ballot(mnew != st.m) != 0ull) {
; #pragma unroll
;     for (int i = 0; i < 16; ++i) { st.o0[i] *= alpha; st.o1[i] *= alpha; }
;   }
;   st.m = mnew;
; #pragma unroll
;   for (int s2 = 0; s2 < 2; ++s2) {
;     u32x4 pk; pk.x = pack2(pr[8 * s2], pr[8 * s2 + 1]); pk.y = pack2(pr[8 * s2 + 2], pr[8 * s2 + 3]); pk.z = pack2(pr[8 * s2 + 4], pr[8 * s2 + 5]); pk.w = pack2(pr[8 * s2 + 6], pr[8 * s2 + 7]);
;     const bf16x8 pb = __builtin_bit_cast(bf16x8, pk);
;     const bf16x8 va0 = __builtin_shufflevector(t.v[s2 * 4 + 0], t.v[s2 * 4 + 1], 0, 1, 2, 3, 4, 5, 6, 7);
;     st.o0 = MFMA32(va0, pb, st.o0);
;     const bf16x8 va1 = __builtin_shufflevector(t.v[s2 * 4 + 2], t.v[s2 * 4 + 3], 0, 1, 2, 3, 4, 5, 6, 7);
;     st.o1 = MFMA32(va1, pb, st.o1);
.Lawin4_softmax:
	v_max3_f32 v118, v32, v33, v34
	v_max3_f32 v119, v40, v41, v42
	v_max3_f32 v120, v48, v49, v50
	v_max3_f32 v121, v56, v57, v58
	v_max3_f32 v118, v118, v35, v36
	v_max3_f32 v119, v119, v43, v44
	v_max3_f32 v120, v120, v51, v52
	v_max3_f32 v121, v121, v59, v60
	v_max3_f32 v118, v118, v37, v38
	v_max3_f32 v119, v119, v45, v46
	v_max3_f32 v120, v120, v53, v54
	v_max3_f32 v121, v121, v61, v62
	v_max_f32_e32 v118, v118, v39
	v_max_f32_e32 v119, v119, v47
	v_max_f32_e32 v120, v120, v55
	v_max_f32_e32 v121, v121, v63
	v_max3_f32 v118, v118, v119, v120
	v_max_f32_e32 v118, v118, v121
	v_mov_b32_e32 v119, v118
	v_mov_b32_e32 v120, v118
	s_nop 1
	v_permlane32_swap_b32_e32 v119, v120
	v_cndmask_b32_e64 v119, v119, v120, s[12:13]
	v_max_f32_e32 v118, v118, v119
	v_cndmask_b32_e64 v118, v199, v118, s[62:63]
	v_max_f32_e32 v119, v145, v118
	v_cmp_neq_f32_e32 vcc, v199, v119
	s_nop 1
	v_cndmask_b32_e32 v120, 0, v119, vcc
	v_sub_f32_e32 v121, v145, v120
	v_exp_f32_e32 v121, v121
	v_cndmask_b32_e64 v120, v181, v120, s[62:63]
	v_cmp_neq_f32_e32 vcc, v145, v119
	v_mov_b32_e32 v145, v119
	v_pk_add_f32 v[32:33], v[32:33], v[120:121] op_sel_hi:[1,0] neg_lo:[0,1] neg_hi:[0,1]
	v_pk_add_f32 v[34:35], v[34:35], v[120:121] op_sel_hi:[1,0] neg_lo:[0,1] neg_hi:[0,1]
	v_pk_add_f32 v[36:37], v[36:37], v[120:121] op_sel_hi:[1,0] neg_lo:[0,1] neg_hi:[0,1]
	v_pk_add_f32 v[38:39], v[38:39], v[120:121] op_sel_hi:[1,0] neg_lo:[0,1] neg_hi:[0,1]
	v_pk_add_f32 v[40:41], v[40:41], v[120:121] op_sel_hi:[1,0] neg_lo:[0,1] neg_hi:[0,1]
	v_pk_add_f32 v[42:43], v[42:43], v[120:121] op_sel_hi:[1,0] neg_lo:[0,1] neg_hi:[0,1]
	v_pk_add_f32 v[44:45], v[44:45], v[120:121] op_sel_hi:[1,0] neg_lo:[0,1] neg_hi:[0,1]
	v_pk_add_f32 v[46:47], v[46:47], v[120:121] op_sel_hi:[1,0] neg_lo:[0,1] neg_hi:[0,1]
	v_pk_add_f32 v[48:49], v[48:49], v[120:121] op_sel_hi:[1,0] neg_lo:[0,1] neg_hi:[0,1]
	v_pk_add_f32 v[50:51], v[50:51], v[120:121] op_sel_hi:[1,0] neg_lo:[0,1] neg_hi:[0,1]
	v_pk_add_f32 v[52:53], v[52:53], v[120:121] op_sel_hi:[1,0] neg_lo:[0,1] neg_hi:[0,1]
	v_pk_add_f32 v[54:55], v[54:55], v[120:121] op_sel_hi:[1,0] neg_lo:[0,1] neg_hi:[0,1]
	v_pk_add_f32 v[56:57], v[56:57], v[120:121] op_sel_hi:[1,0] neg_lo:[0,1] neg_hi:[0,1]
	v_pk_add_f32 v[58:59], v[58:59], v[120:121] op_sel_hi:[1,0] neg_lo:[0,1] neg_hi:[0,1]
	v_pk_add_f32 v[60:61], v[60:61], v[120:121] op_sel_hi:[1,0] neg_lo:[0,1] neg_hi:[0,1]
	v_pk_add_f32 v[62:63], v[62:63], v[120:121] op_sel_hi:[1,0] neg_lo:[0,1] neg_hi:[0,1]
	v_exp_f32_e32 v32, v32
	v_exp_f32_e32 v33, v33
	v_exp_f32_e32 v34, v34
	v_exp_f32_e32 v35, v35
	v_exp_f32_e32 v36, v36
	v_exp_f32_e32 v37, v37
	v_exp_f32_e32 v38, v38
	v_exp_f32_e32 v39, v39
	v_exp_f32_e32 v40, v40
	v_exp_f32_e32 v41, v41
	v_exp_f32_e32 v42, v42
	v_exp_f32_e32 v43, v43
	v_exp_f32_e32 v44, v44
	v_exp_f32_e32 v45, v45
	v_exp_f32_e32 v46, v46
	v_exp_f32_e32 v47, v47
	v_exp_f32_e32 v48, v48
	v_exp_f32_e32 v49, v49
	v_exp_f32_e32 v50, v50
	v_exp_f32_e32 v51, v51
	v_exp_f32_e32 v52, v52
	v_exp_f32_e32 v53, v53
	v_exp_f32_e32 v54, v54
	v_exp_f32_e32 v55, v55
	v_exp_f32_e32 v56, v56
	v_exp_f32_e32 v57, v57
	v_exp_f32_e32 v58, v58
	v_exp_f32_e32 v59, v59
	v_exp_f32_e32 v60, v60
	v_exp_f32_e32 v61, v61
	v_exp_f32_e32 v62, v62
	v_exp_f32_e32 v63, v63
	v_pk_add_f32 v[122:123], v[32:33], v[34:35]
	v_pk_add_f32 v[124:125], v[36:37], v[38:39]
	v_pk_add_f32 v[122:123], v[122:123], v[40:41]
	v_pk_add_f32 v[124:125], v[124:125], v[42:43]
	v_pk_add_f32 v[122:123], v[122:123], v[44:45]
	v_pk_add_f32 v[124:125], v[124:125], v[46:47]
	v_pk_add_f32 v[122:123], v[122:123], v[48:49]
	v_pk_add_f32 v[124:125], v[124:125], v[50:51]
	v_pk_add_f32 v[122:123], v[122:123], v[52:53]
	v_pk_add_f32 v[124:125], v[124:125], v[54:55]
	v_pk_add_f32 v[122:123], v[122:123], v[56:57]
	v_pk_add_f32 v[124:125], v[124:125], v[58:59]
	v_pk_add_f32 v[122:123], v[122:123], v[60:61]
	v_pk_add_f32 v[124:125], v[124:125], v[62:63]
	v_pk_add_f32 v[122:123], v[122:123], v[124:125]
	v_add_f32_e32 v122, v122, v123
	v_fma_f32 v144, v144, v121, v122
	s_cbranch_vccz .Lawin4_noscale
	v_pk_mul_f32 v[0:1], v[0:1], v[120:121] op_sel:[0,1] op_sel_hi:[1,1]
	v_pk_mul_f32 v[2:3], v[2:3], v[120:121] op_sel:[0,1] op_sel_hi:[1,1]
	v_pk_mul_f32 v[4:5], v[4:5], v[120:121] op_sel:[0,1] op_sel_hi:[1,1]
	v_pk_mul_f32 v[6:7], v[6:7], v[120:121] op_sel:[0,1] op_sel_hi:[1,1]
	v_pk_mul_f32 v[8:9], v[8:9], v[120:121] op_sel:[0,1] op_sel_hi:[1,1]
	v_pk_mul_f32 v[10:11], v[10:11], v[120:121] op_sel:[0,1] op_sel_hi:[1,1]
	v_pk_mul_f32 v[12:13], v[12:13], v[120:121] op_sel:[0,1] op_sel_hi:[1,1]
	v_pk_mul_f32 v[14:15], v[14:15], v[120:121] op_sel:[0,1] op_sel_hi:[1,1]
	v_pk_mul_f32 v[16:17], v[16:17], v[120:121] op_sel:[0,1] op_sel_hi:[1,1]
	v_pk_mul_f32 v[18:19], v[18:19], v[120:121] op_sel:[0,1] op_sel_hi:[1,1]
	v_pk_mul_f32 v[20:21], v[20:21], v[120:121] op_sel:[0,1] op_sel_hi:[1,1]
	v_pk_mul_f32 v[22:23], v[22:23], v[120:121] op_sel:[0,1] op_sel_hi:[1,1]
	v_pk_mul_f32 v[24:25], v[24:25], v[120:121] op_sel:[0,1] op_sel_hi:[1,1]
	v_pk_mul_f32 v[26:27], v[26:27], v[120:121] op_sel:[0,1] op_sel_hi:[1,1]
	v_pk_mul_f32 v[28:29], v[28:29], v[120:121] op_sel:[0,1] op_sel_hi:[1,1]
	v_pk_mul_f32 v[30:31], v[30:31], v[120:121] op_sel:[0,1] op_sel_hi:[1,1]
